# as diet3c + input-projection epilogue: sigmoid/silu add/mul pairs as packed f32 ops (bit-identical), b_gate values loaded once per tile
# baseline (speedup 1.0000x reference)
; #define GAS __attribute__((address_space(1)))
; __device__ __forceinline__ float sigmoidf_(float x) { return frcp(1.f + fexp2(-x * LOG2E)); }
; __device__ __forceinline__ float siluf_(float x) { return x * sigmoidf_(x); }
; __device__ __forceinline__ u32x4 pack8(f32x4 a, f32x4 b) { u32x4 w; w.x = pk2(a[0], a[1]); w.y = pk2(a[2], a[3]); w.z = pk2(b[0], b[1]); w.w = pk2(b[2], b[3]); return w; }
;     __device__ __forceinline__ void operator()(const Unit& u, int row, int col, f32x4 v0, f32x4 v1) const {
;         const int pn = u.pn;
;         if (pn < 2) {
;             const int c = pn * 256 + col, g = c >> 4, p = c & 15;
;             *(GAS u32x4*)(Ap + ((size_t)(g * 2048 + (row >> 4)) * 512 + (row & 15) * 16 + p)) = pack8(v0, v1);
;         } else if (pn < 22) {
;             const int pc = pn * 256 - 512 + col;
;             if (pn >= 10) {
;                 const f32x4 b0 = *(const GAS f32x4*)(b_gate + pc - PC_GATE), b1 = *(const GAS f32x4*)(b_gate + pc - PC_GATE + 4);
; #pragma unroll
;                 for (int i = 0; i < 4; ++i) { v0[i] = sigmoidf_(v0[i] + b0[i]); v1[i] = sigmoidf_(v1[i] + b1[i]); }
;             } else if (pn == 8 || pn == 9) {
;                 const float sc = 0.08838834764831845f * LOG2E;
;                 v0 = v0 * sc; v1 = v1 * sc;
;             } else {
; #pragma unroll
;                 for (int i = 0; i < 4; ++i) { v0[i] = siluf_(v0[i]); v1[i] = siluf_(v1[i]); }
.LBB0_186:
	s_mov_b32 s98, 0xbfb8aa3b
	s_mov_b32 s100, 1.0
	s_lshl_b32 s57, s6, 8
	s_add_i32 s57, s57, s85
	s_cmp_gt_i32 s76, 1
	s_cselect_b64 s[6:7], -1, 0
	s_cmp_gt_u32 s76, 21
	s_cselect_b64 s[74:75], -1, 0
	s_lshl_b32 s68, s76, 8
	s_add_i32 s38, s68, 0xffffea00
	s_cmp_lt_u32 s76, 10
	v_or_b32_e32 v150, s57, v162
	s_cselect_b64 s[72:73], -1, 0
	s_and_b32 s8, s76, 14
	v_ashrrev_i32_e32 v151, 31, v150
	s_cmp_lg_u32 s8, 8
	v_lshlrev_b64 v[152:153], 10, v[150:151]
	v_mad_i64_i32 v[150:151], s[8:9], v150, s10, 0
	s_cselect_b64 s[70:71], -1, 0
	s_andn2_b64 s[8:9], s[6:7], s[74:75]
	s_andn2_b64 s[8:9], s[8:9], s[72:73]
	s_and_b64 vcc, exec, s[8:9]
	s_cbranch_vccz .Lfproj_nogate
	s_ashr_i32 s69, s68, 31
	v_lshl_add_u64 v[196:197], s[68:69], 0, v[136:137]
	v_lshl_add_u64 v[204:205], s[68:69], 0, v[138:139]
	s_waitcnt lgkmcnt(0)
	v_lshl_add_u64 v[196:197], v[196:197], 2, s[36:37]
	v_lshl_add_u64 v[204:205], v[204:205], 2, s[36:37]
	v_lshl_add_u64 v[200:201], v[196:197], 0, s[54:55]
	v_lshl_add_u64 v[208:209], v[204:205], 0, s[54:55]
	v_add_co_u32_e32 v196, vcc, 0xffffe000, v196
	s_nop 1
	v_addc_co_u32_e32 v197, vcc, -1, v197, vcc
	v_add_co_u32_e32 v204, vcc, 0xffffe000, v204
	s_nop 1
	v_addc_co_u32_e32 v205, vcc, -1, v205, vcc
	global_load_dwordx4 v[196:199], v[196:197], off offset:-2048
	global_load_dwordx4 v[200:203], v[200:201], off offset:16
	global_load_dwordx4 v[204:207], v[204:205], off offset:-2048
	global_load_dwordx4 v[208:211], v[208:209], off offset:16
.Lfproj_nogate:
	s_mov_b64 s[8:9], -1
	s_and_b64 vcc, exec, s[6:7]
	s_cbranch_vccz .LBB0_200
	s_and_b64 vcc, exec, s[74:75]
	s_cbranch_vccz .LBB0_189
	v_lshl_add_u64 v[158:159], s[44:45], 0, v[152:153]
	v_lshl_add_u64 v[158:159], s[38:39], 1, v[158:159]
	v_cvt_pk_bf16_f32 v154, v120, v121
	v_cvt_pk_bf16_f32 v155, v122, v123
	v_cvt_pk_bf16_f32 v156, v124, v125
	v_cvt_pk_bf16_f32 v157, v126, v127
	v_lshl_add_u64 v[158:159], v[136:137], 1, v[158:159]
	global_store_dwordx4 v[158:159], v[154:157], off
	s_mov_b64 s[8:9], 0
.LBB0_189:
	s_andn2_b64 vcc, exec, s[8:9]
	s_cbranch_vccnz .LBB0_199
	s_mov_b64 s[8:9], -1
	s_and_b64 vcc, exec, s[72:73]
	s_cbranch_vccz .LBB0_196
	s_andn2_b64 vcc, exec, s[70:71]
	s_cbranch_vccnz .LBB0_193
	s_mov_b64 s[8:9], 0
	v_pk_mul_f32 v[212:213], v[120:121], s[98:99] op_sel_hi:[1,0]
	v_pk_mul_f32 v[214:215], v[122:123], s[98:99] op_sel_hi:[1,0]
	v_pk_mul_f32 v[216:217], v[126:127], s[98:99] op_sel_hi:[1,0]
	v_pk_mul_f32 v[218:219], v[124:125], s[98:99] op_sel_hi:[1,0]
	v_exp_f32_e32 v212, v212
	v_exp_f32_e32 v213, v213
	v_exp_f32_e32 v214, v214
	v_exp_f32_e32 v215, v215
	v_exp_f32_e32 v216, v216
	v_exp_f32_e32 v217, v217
	v_exp_f32_e32 v218, v218
	v_exp_f32_e32 v219, v219
	v_pk_add_f32 v[212:213], v[212:213], s[100:101] op_sel_hi:[1,0]
	v_pk_add_f32 v[214:215], v[214:215], s[100:101] op_sel_hi:[1,0]
	v_pk_add_f32 v[216:217], v[216:217], s[100:101] op_sel_hi:[1,0]
	v_pk_add_f32 v[218:219], v[218:219], s[100:101] op_sel_hi:[1,0]
	v_rcp_f32_e32 v212, v212
	v_rcp_f32_e32 v213, v213
	v_rcp_f32_e32 v214, v214
	v_rcp_f32_e32 v215, v215
	v_rcp_f32_e32 v216, v216
	v_rcp_f32_e32 v217, v217
	v_rcp_f32_e32 v218, v218
	v_rcp_f32_e32 v219, v219
	v_pk_mul_f32 v[156:157], v[120:121], v[212:213]
	v_pk_mul_f32 v[154:155], v[122:123], v[214:215]
	v_pk_mul_f32 v[158:159], v[126:127], v[216:217]
	v_pk_mul_f32 v[160:161], v[124:125], v[218:219]

; #define GAS __attribute__((address_space(1)))
; __device__ __forceinline__ float sigmoidf_(float x) { return frcp(1.f + fexp2(-x * LOG2E)); }
;     __device__ __forceinline__ void operator()(const Unit& u, int row, int col, f32x4 v0, f32x4 v1) const {
;     ...
;             if (pn >= 10) {
;                 const f32x4 b0 = *(const GAS f32x4*)(b_gate + pc - PC_GATE), b1 = *(const GAS f32x4*)(b_gate + pc - PC_GATE + 4);
; #pragma unroll
;                 for (int i = 0; i < 4; ++i) { v0[i] = sigmoidf_(v0[i] + b0[i]); v1[i] = sigmoidf_(v1[i] + b1[i]); }
.LBB0_196:
	s_andn2_b64 vcc, exec, s[8:9]
	s_cbranch_vccnz .LBB0_198
	s_waitcnt vmcnt(2)
	v_pk_add_f32 v[212:213], v[120:121], v[196:197]
	v_pk_add_f32 v[214:215], v[122:123], v[198:199]
	v_pk_add_f32 v[216:217], v[124:125], v[200:201]
	v_pk_add_f32 v[218:219], v[126:127], v[202:203]
	v_pk_mul_f32 v[212:213], v[212:213], s[98:99] op_sel_hi:[1,0]
	v_pk_mul_f32 v[214:215], v[214:215], s[98:99] op_sel_hi:[1,0]
	v_pk_mul_f32 v[216:217], v[216:217], s[98:99] op_sel_hi:[1,0]
	v_pk_mul_f32 v[218:219], v[218:219], s[98:99] op_sel_hi:[1,0]
	v_exp_f32_e32 v212, v212
	v_exp_f32_e32 v213, v213
	v_exp_f32_e32 v214, v214
	v_exp_f32_e32 v215, v215
	v_exp_f32_e32 v216, v216
	v_exp_f32_e32 v217, v217
	v_exp_f32_e32 v218, v218
	v_exp_f32_e32 v219, v219
	v_pk_add_f32 v[212:213], v[212:213], s[100:101] op_sel_hi:[1,0]
	v_pk_add_f32 v[214:215], v[214:215], s[100:101] op_sel_hi:[1,0]
	v_pk_add_f32 v[216:217], v[216:217], s[100:101] op_sel_hi:[1,0]
	v_pk_add_f32 v[218:219], v[218:219], s[100:101] op_sel_hi:[1,0]
	v_rcp_f32_e32 v156, v212
	v_rcp_f32_e32 v157, v213
	v_rcp_f32_e32 v154, v214
	v_rcp_f32_e32 v155, v215
	v_rcp_f32_e32 v160, v216
	v_rcp_f32_e32 v161, v217
	v_rcp_f32_e32 v158, v218
	v_rcp_f32_e32 v159, v219

; __device__ __forceinline__ float siluf_(float x) { return x * sigmoidf_(x); }
;     __device__ __forceinline__ void operator()(const Unit& u, int row, int col, f32x4 v0, f32x4 v1) const {
;     ...
; #pragma unroll
;                 for (int i = 0; i < 4; ++i) { v0[i] = siluf_(v0[i]); v1[i] = siluf_(v1[i]); }
.LBB0_205:
	s_andn2_b64 vcc, exec, s[74:75]
	s_cbranch_vccnz .LBB0_215
	s_andn2_b64 vcc, exec, s[72:73]
	s_mov_b64 s[74:75], -1
	s_cbranch_vccnz .LBB0_212
	s_andn2_b64 vcc, exec, s[70:71]
	s_cbranch_vccnz .LBB0_209
	s_mov_b64 s[74:75], 0
	v_pk_mul_f32 v[212:213], v[116:117], s[98:99] op_sel_hi:[1,0]
	v_pk_mul_f32 v[214:215], v[118:119], s[98:99] op_sel_hi:[1,0]
	v_pk_mul_f32 v[216:217], v[114:115], s[98:99] op_sel_hi:[1,0]
	v_pk_mul_f32 v[218:219], v[112:113], s[98:99] op_sel_hi:[1,0]
	v_exp_f32_e32 v212, v212
	v_exp_f32_e32 v213, v213
	v_exp_f32_e32 v214, v214
	v_exp_f32_e32 v215, v215
	v_exp_f32_e32 v216, v216
	v_exp_f32_e32 v217, v217
	v_exp_f32_e32 v218, v218
	v_exp_f32_e32 v219, v219
	v_pk_add_f32 v[212:213], v[212:213], s[100:101] op_sel_hi:[1,0]
	v_pk_add_f32 v[214:215], v[214:215], s[100:101] op_sel_hi:[1,0]
	v_pk_add_f32 v[216:217], v[216:217], s[100:101] op_sel_hi:[1,0]
	v_pk_add_f32 v[218:219], v[218:219], s[100:101] op_sel_hi:[1,0]
	v_rcp_f32_e32 v212, v212
	v_rcp_f32_e32 v213, v213
	v_rcp_f32_e32 v214, v214
	v_rcp_f32_e32 v215, v215
	v_rcp_f32_e32 v216, v216
	v_rcp_f32_e32 v217, v217
	v_rcp_f32_e32 v218, v218
	v_rcp_f32_e32 v219, v219
	v_pk_mul_f32 v[122:123], v[116:117], v[212:213]
	v_pk_mul_f32 v[120:121], v[118:119], v[214:215]
	v_pk_mul_f32 v[124:125], v[114:115], v[216:217]
	v_pk_mul_f32 v[126:127], v[112:113], v[218:219]

; #define GAS __attribute__((address_space(1)))
; __device__ __forceinline__ float sigmoidf_(float x) { return frcp(1.f + fexp2(-x * LOG2E)); }
;     __device__ __forceinline__ void operator()(const Unit& u, int row, int col, f32x4 v0, f32x4 v1) const {
;     ...
;             if (pn >= 10) {
;                 const f32x4 b0 = *(const GAS f32x4*)(b_gate + pc - PC_GATE), b1 = *(const GAS f32x4*)(b_gate + pc - PC_GATE + 4);
; #pragma unroll
;                 for (int i = 0; i < 4; ++i) { v0[i] = sigmoidf_(v0[i] + b0[i]); v1[i] = sigmoidf_(v1[i] + b1[i]); }
.LBB0_212:
	s_andn2_b64 vcc, exec, s[74:75]
	s_cbranch_vccnz .LBB0_214
	s_waitcnt vmcnt(1)
	v_pk_add_f32 v[212:213], v[112:113], v[208:209]
	v_pk_add_f32 v[214:215], v[114:115], v[210:211]
	v_pk_add_f32 v[216:217], v[116:117], v[204:205]
	v_pk_add_f32 v[218:219], v[118:119], v[206:207]
	v_pk_mul_f32 v[212:213], v[212:213], s[98:99] op_sel_hi:[1,0]
	v_pk_mul_f32 v[214:215], v[214:215], s[98:99] op_sel_hi:[1,0]
	v_pk_mul_f32 v[216:217], v[216:217], s[98:99] op_sel_hi:[1,0]
	v_pk_mul_f32 v[218:219], v[218:219], s[98:99] op_sel_hi:[1,0]
	v_exp_f32_e32 v212, v212
	v_exp_f32_e32 v213, v213
	v_exp_f32_e32 v214, v214
	v_exp_f32_e32 v215, v215
	v_exp_f32_e32 v216, v216
	v_exp_f32_e32 v217, v217
	v_exp_f32_e32 v218, v218
	v_exp_f32_e32 v219, v219
	v_pk_add_f32 v[212:213], v[212:213], s[100:101] op_sel_hi:[1,0]
	v_pk_add_f32 v[214:215], v[214:215], s[100:101] op_sel_hi:[1,0]
	v_pk_add_f32 v[216:217], v[216:217], s[100:101] op_sel_hi:[1,0]
	v_pk_add_f32 v[218:219], v[218:219], s[100:101] op_sel_hi:[1,0]
	v_rcp_f32_e32 v126, v212
	v_rcp_f32_e32 v127, v213
	v_rcp_f32_e32 v124, v214
	v_rcp_f32_e32 v125, v215
	v_rcp_f32_e32 v122, v216
	v_rcp_f32_e32 v123, v217
	v_rcp_f32_e32 v120, v218
	v_rcp_f32_e32 v121, v219

; __device__ __forceinline__ float siluf_(float x) { return x * sigmoidf_(x); }
;     __device__ __forceinline__ void operator()(const Unit& u, int row, int col, f32x4 v0, f32x4 v1) const {
;     ...
; #pragma unroll
;                 for (int i = 0; i < 4; ++i) { v0[i] = siluf_(v0[i]); v1[i] = siluf_(v1[i]); }
.LBB0_221:
	s_andn2_b64 vcc, exec, s[74:75]
	s_cbranch_vccnz .LBB0_231
	s_andn2_b64 vcc, exec, s[72:73]
	s_mov_b64 s[74:75], -1
	s_cbranch_vccnz .LBB0_228
	s_andn2_b64 vcc, exec, s[70:71]
	s_cbranch_vccnz .LBB0_225
	s_mov_b64 s[74:75], 0
	v_pk_mul_f32 v[212:213], v[108:109], s[98:99] op_sel_hi:[1,0]
	v_pk_mul_f32 v[214:215], v[110:111], s[98:99] op_sel_hi:[1,0]
	v_pk_mul_f32 v[216:217], v[106:107], s[98:99] op_sel_hi:[1,0]
	v_pk_mul_f32 v[218:219], v[104:105], s[98:99] op_sel_hi:[1,0]
	v_exp_f32_e32 v212, v212
	v_exp_f32_e32 v213, v213
	v_exp_f32_e32 v214, v214
	v_exp_f32_e32 v215, v215
	v_exp_f32_e32 v216, v216
	v_exp_f32_e32 v217, v217
	v_exp_f32_e32 v218, v218
	v_exp_f32_e32 v219, v219
	v_pk_add_f32 v[212:213], v[212:213], s[100:101] op_sel_hi:[1,0]
	v_pk_add_f32 v[214:215], v[214:215], s[100:101] op_sel_hi:[1,0]
	v_pk_add_f32 v[216:217], v[216:217], s[100:101] op_sel_hi:[1,0]
	v_pk_add_f32 v[218:219], v[218:219], s[100:101] op_sel_hi:[1,0]
	v_rcp_f32_e32 v212, v212
	v_rcp_f32_e32 v213, v213
	v_rcp_f32_e32 v214, v214
	v_rcp_f32_e32 v215, v215
	v_rcp_f32_e32 v216, v216
	v_rcp_f32_e32 v217, v217
	v_rcp_f32_e32 v218, v218
	v_rcp_f32_e32 v219, v219
	v_pk_mul_f32 v[118:119], v[108:109], v[212:213]
	v_pk_mul_f32 v[116:117], v[110:111], v[214:215]
	v_pk_mul_f32 v[120:121], v[106:107], v[216:217]
	v_pk_mul_f32 v[122:123], v[104:105], v[218:219]

; #define GAS __attribute__((address_space(1)))
; __device__ __forceinline__ float sigmoidf_(float x) { return frcp(1.f + fexp2(-x * LOG2E)); }
;     __device__ __forceinline__ void operator()(const Unit& u, int row, int col, f32x4 v0, f32x4 v1) const {
;     ...
;             if (pn >= 10) {
;                 const f32x4 b0 = *(const GAS f32x4*)(b_gate + pc - PC_GATE), b1 = *(const GAS f32x4*)(b_gate + pc - PC_GATE + 4);
; #pragma unroll
;                 for (int i = 0; i < 4; ++i) { v0[i] = sigmoidf_(v0[i] + b0[i]); v1[i] = sigmoidf_(v1[i] + b1[i]); }
.LBB0_228:
	s_andn2_b64 vcc, exec, s[74:75]
	s_cbranch_vccnz .LBB0_230
	v_pk_add_f32 v[212:213], v[104:105], v[200:201]
	v_pk_add_f32 v[214:215], v[106:107], v[202:203]
	v_pk_add_f32 v[216:217], v[108:109], v[196:197]
	v_pk_add_f32 v[218:219], v[110:111], v[198:199]
	v_pk_mul_f32 v[212:213], v[212:213], s[98:99] op_sel_hi:[1,0]
	v_pk_mul_f32 v[214:215], v[214:215], s[98:99] op_sel_hi:[1,0]
	v_pk_mul_f32 v[216:217], v[216:217], s[98:99] op_sel_hi:[1,0]
	v_pk_mul_f32 v[218:219], v[218:219], s[98:99] op_sel_hi:[1,0]
	v_exp_f32_e32 v212, v212
	v_exp_f32_e32 v213, v213
	v_exp_f32_e32 v214, v214
	v_exp_f32_e32 v215, v215
	v_exp_f32_e32 v216, v216
	v_exp_f32_e32 v217, v217
	v_exp_f32_e32 v218, v218
	v_exp_f32_e32 v219, v219
	v_pk_add_f32 v[212:213], v[212:213], s[100:101] op_sel_hi:[1,0]
	v_pk_add_f32 v[214:215], v[214:215], s[100:101] op_sel_hi:[1,0]
	v_pk_add_f32 v[216:217], v[216:217], s[100:101] op_sel_hi:[1,0]
	v_pk_add_f32 v[218:219], v[218:219], s[100:101] op_sel_hi:[1,0]
	v_rcp_f32_e32 v122, v212
	v_rcp_f32_e32 v123, v213
	v_rcp_f32_e32 v120, v214
	v_rcp_f32_e32 v121, v215
	v_rcp_f32_e32 v118, v216
	v_rcp_f32_e32 v119, v217
	v_rcp_f32_e32 v116, v218
	v_rcp_f32_e32 v117, v219

; __device__ __forceinline__ float siluf_(float x) { return x * sigmoidf_(x); }
;     __device__ __forceinline__ void operator()(const Unit& u, int row, int col, f32x4 v0, f32x4 v1) const {
;     ...
; #pragma unroll
;                 for (int i = 0; i < 4; ++i) { v0[i] = siluf_(v0[i]); v1[i] = siluf_(v1[i]); }
.LBB0_235:
	s_andn2_b64 vcc, exec, s[74:75]
	s_cbranch_vccnz .LBB0_245
	s_andn2_b64 vcc, exec, s[72:73]
	s_mov_b64 s[74:75], -1
	s_cbranch_vccnz .LBB0_242
	s_andn2_b64 vcc, exec, s[70:71]
	s_cbranch_vccnz .LBB0_239
	s_mov_b64 s[74:75], 0
	v_pk_mul_f32 v[212:213], v[100:101], s[98:99] op_sel_hi:[1,0]
	v_pk_mul_f32 v[214:215], v[102:103], s[98:99] op_sel_hi:[1,0]
	v_pk_mul_f32 v[216:217], v[98:99], s[98:99] op_sel_hi:[1,0]
	v_pk_mul_f32 v[218:219], v[96:97], s[98:99] op_sel_hi:[1,0]
	v_exp_f32_e32 v212, v212
	v_exp_f32_e32 v213, v213
	v_exp_f32_e32 v214, v214
	v_exp_f32_e32 v215, v215
	v_exp_f32_e32 v216, v216
	v_exp_f32_e32 v217, v217
	v_exp_f32_e32 v218, v218
	v_exp_f32_e32 v219, v219
	v_pk_add_f32 v[212:213], v[212:213], s[100:101] op_sel_hi:[1,0]
	v_pk_add_f32 v[214:215], v[214:215], s[100:101] op_sel_hi:[1,0]
	v_pk_add_f32 v[216:217], v[216:217], s[100:101] op_sel_hi:[1,0]
	v_pk_add_f32 v[218:219], v[218:219], s[100:101] op_sel_hi:[1,0]
	v_rcp_f32_e32 v212, v212
	v_rcp_f32_e32 v213, v213
	v_rcp_f32_e32 v214, v214
	v_rcp_f32_e32 v215, v215
	v_rcp_f32_e32 v216, v216
	v_rcp_f32_e32 v217, v217
	v_rcp_f32_e32 v218, v218
	v_rcp_f32_e32 v219, v219
	v_pk_mul_f32 v[106:107], v[100:101], v[212:213]
	v_pk_mul_f32 v[104:105], v[102:103], v[214:215]
	v_pk_mul_f32 v[108:109], v[98:99], v[216:217]
	v_pk_mul_f32 v[110:111], v[96:97], v[218:219]

; #define GAS __attribute__((address_space(1)))
; __device__ __forceinline__ float sigmoidf_(float x) { return frcp(1.f + fexp2(-x * LOG2E)); }
;     __device__ __forceinline__ void operator()(const Unit& u, int row, int col, f32x4 v0, f32x4 v1) const {
;     ...
;             if (pn >= 10) {
;                 const f32x4 b0 = *(const GAS f32x4*)(b_gate + pc - PC_GATE), b1 = *(const GAS f32x4*)(b_gate + pc - PC_GATE + 4);
; #pragma unroll
;                 for (int i = 0; i < 4; ++i) { v0[i] = sigmoidf_(v0[i] + b0[i]); v1[i] = sigmoidf_(v1[i] + b1[i]); }
.LBB0_242:
	s_andn2_b64 vcc, exec, s[74:75]
	s_cbranch_vccnz .LBB0_244
	v_pk_add_f32 v[212:213], v[96:97], v[208:209]
	v_pk_add_f32 v[214:215], v[98:99], v[210:211]
	v_pk_add_f32 v[216:217], v[100:101], v[204:205]
	v_pk_add_f32 v[218:219], v[102:103], v[206:207]
	v_pk_mul_f32 v[212:213], v[212:213], s[98:99] op_sel_hi:[1,0]
	v_pk_mul_f32 v[214:215], v[214:215], s[98:99] op_sel_hi:[1,0]
	v_pk_mul_f32 v[216:217], v[216:217], s[98:99] op_sel_hi:[1,0]
	v_pk_mul_f32 v[218:219], v[218:219], s[98:99] op_sel_hi:[1,0]
	v_exp_f32_e32 v212, v212
	v_exp_f32_e32 v213, v213
	v_exp_f32_e32 v214, v214
	v_exp_f32_e32 v215, v215
	v_exp_f32_e32 v216, v216
	v_exp_f32_e32 v217, v217
	v_exp_f32_e32 v218, v218
	v_exp_f32_e32 v219, v219
	v_pk_add_f32 v[212:213], v[212:213], s[100:101] op_sel_hi:[1,0]
	v_pk_add_f32 v[214:215], v[214:215], s[100:101] op_sel_hi:[1,0]
	v_pk_add_f32 v[216:217], v[216:217], s[100:101] op_sel_hi:[1,0]
	v_pk_add_f32 v[218:219], v[218:219], s[100:101] op_sel_hi:[1,0]
	v_rcp_f32_e32 v110, v212
	v_rcp_f32_e32 v111, v213
	v_rcp_f32_e32 v108, v214
	v_rcp_f32_e32 v109, v215
	v_rcp_f32_e32 v106, v216
	v_rcp_f32_e32 v107, v217
	v_rcp_f32_e32 v104, v218
	v_rcp_f32_e32 v105, v219

; __device__ __forceinline__ float siluf_(float x) { return x * sigmoidf_(x); }
;     __device__ __forceinline__ void operator()(const Unit& u, int row, int col, f32x4 v0, f32x4 v1) const {
;     ...
; #pragma unroll
;                 for (int i = 0; i < 4; ++i) { v0[i] = siluf_(v0[i]); v1[i] = siluf_(v1[i]); }
.LBB0_253:
	s_andn2_b64 vcc, exec, s[74:75]
	s_cbranch_vccnz .LBB0_263
	s_andn2_b64 vcc, exec, s[72:73]
	s_mov_b64 s[74:75], -1
	s_cbranch_vccnz .LBB0_260
	s_andn2_b64 vcc, exec, s[70:71]
	s_cbranch_vccnz .LBB0_257
	s_mov_b64 s[74:75], 0
	v_pk_mul_f32 v[212:213], v[92:93], s[98:99] op_sel_hi:[1,0]
	v_pk_mul_f32 v[214:215], v[94:95], s[98:99] op_sel_hi:[1,0]
	v_pk_mul_f32 v[216:217], v[90:91], s[98:99] op_sel_hi:[1,0]
	v_pk_mul_f32 v[218:219], v[88:89], s[98:99] op_sel_hi:[1,0]
	v_exp_f32_e32 v212, v212
	v_exp_f32_e32 v213, v213
	v_exp_f32_e32 v214, v214
	v_exp_f32_e32 v215, v215
	v_exp_f32_e32 v216, v216
	v_exp_f32_e32 v217, v217
	v_exp_f32_e32 v218, v218
	v_exp_f32_e32 v219, v219
	v_pk_add_f32 v[212:213], v[212:213], s[100:101] op_sel_hi:[1,0]
	v_pk_add_f32 v[214:215], v[214:215], s[100:101] op_sel_hi:[1,0]
	v_pk_add_f32 v[216:217], v[216:217], s[100:101] op_sel_hi:[1,0]
	v_pk_add_f32 v[218:219], v[218:219], s[100:101] op_sel_hi:[1,0]
	v_rcp_f32_e32 v212, v212
	v_rcp_f32_e32 v213, v213
	v_rcp_f32_e32 v214, v214
	v_rcp_f32_e32 v215, v215
	v_rcp_f32_e32 v216, v216
	v_rcp_f32_e32 v217, v217
	v_rcp_f32_e32 v218, v218
	v_rcp_f32_e32 v219, v219
	v_pk_mul_f32 v[102:103], v[92:93], v[212:213]
	v_pk_mul_f32 v[100:101], v[94:95], v[214:215]
	v_pk_mul_f32 v[104:105], v[90:91], v[216:217]
	v_pk_mul_f32 v[106:107], v[88:89], v[218:219]

; #define GAS __attribute__((address_space(1)))
; __device__ __forceinline__ float sigmoidf_(float x) { return frcp(1.f + fexp2(-x * LOG2E)); }
;     __device__ __forceinline__ void operator()(const Unit& u, int row, int col, f32x4 v0, f32x4 v1) const {
;     ...
;             if (pn >= 10) {
;                 const f32x4 b0 = *(const GAS f32x4*)(b_gate + pc - PC_GATE), b1 = *(const GAS f32x4*)(b_gate + pc - PC_GATE + 4);
; #pragma unroll
;                 for (int i = 0; i < 4; ++i) { v0[i] = sigmoidf_(v0[i] + b0[i]); v1[i] = sigmoidf_(v1[i] + b1[i]); }
.LBB0_260:
	s_andn2_b64 vcc, exec, s[74:75]
	s_cbranch_vccnz .LBB0_262
	v_pk_add_f32 v[212:213], v[88:89], v[200:201]
	v_pk_add_f32 v[214:215], v[90:91], v[202:203]
	v_pk_add_f32 v[216:217], v[92:93], v[196:197]
	v_pk_add_f32 v[218:219], v[94:95], v[198:199]
	v_pk_mul_f32 v[212:213], v[212:213], s[98:99] op_sel_hi:[1,0]
	v_pk_mul_f32 v[214:215], v[214:215], s[98:99] op_sel_hi:[1,0]
	v_pk_mul_f32 v[216:217], v[216:217], s[98:99] op_sel_hi:[1,0]
	v_pk_mul_f32 v[218:219], v[218:219], s[98:99] op_sel_hi:[1,0]
	v_exp_f32_e32 v212, v212
	v_exp_f32_e32 v213, v213
	v_exp_f32_e32 v214, v214
	v_exp_f32_e32 v215, v215
	v_exp_f32_e32 v216, v216
	v_exp_f32_e32 v217, v217
	v_exp_f32_e32 v218, v218
	v_exp_f32_e32 v219, v219
	v_pk_add_f32 v[212:213], v[212:213], s[100:101] op_sel_hi:[1,0]
	v_pk_add_f32 v[214:215], v[214:215], s[100:101] op_sel_hi:[1,0]
	v_pk_add_f32 v[216:217], v[216:217], s[100:101] op_sel_hi:[1,0]
	v_pk_add_f32 v[218:219], v[218:219], s[100:101] op_sel_hi:[1,0]
	v_rcp_f32_e32 v106, v212
	v_rcp_f32_e32 v107, v213
	v_rcp_f32_e32 v104, v214
	v_rcp_f32_e32 v105, v215
	v_rcp_f32_e32 v102, v216
	v_rcp_f32_e32 v103, v217
	v_rcp_f32_e32 v100, v218
	v_rcp_f32_e32 v101, v219

; __device__ __forceinline__ float siluf_(float x) { return x * sigmoidf_(x); }
;     __device__ __forceinline__ void operator()(const Unit& u, int row, int col, f32x4 v0, f32x4 v1) const {
;     ...
; #pragma unroll
;                 for (int i = 0; i < 4; ++i) { v0[i] = siluf_(v0[i]); v1[i] = siluf_(v1[i]); }
.LBB0_267:
	s_andn2_b64 vcc, exec, s[74:75]
	s_cbranch_vccnz .LBB0_277
	s_andn2_b64 vcc, exec, s[72:73]
	s_mov_b64 s[74:75], -1
	s_cbranch_vccnz .LBB0_274
	s_andn2_b64 vcc, exec, s[70:71]
	s_cbranch_vccnz .LBB0_271
	s_mov_b64 s[74:75], 0
	v_pk_mul_f32 v[212:213], v[84:85], s[98:99] op_sel_hi:[1,0]
	v_pk_mul_f32 v[214:215], v[86:87], s[98:99] op_sel_hi:[1,0]
	v_pk_mul_f32 v[216:217], v[82:83], s[98:99] op_sel_hi:[1,0]
	v_pk_mul_f32 v[218:219], v[80:81], s[98:99] op_sel_hi:[1,0]
	v_exp_f32_e32 v212, v212
	v_exp_f32_e32 v213, v213
	v_exp_f32_e32 v214, v214
	v_exp_f32_e32 v215, v215
	v_exp_f32_e32 v216, v216
	v_exp_f32_e32 v217, v217
	v_exp_f32_e32 v218, v218
	v_exp_f32_e32 v219, v219
	v_pk_add_f32 v[212:213], v[212:213], s[100:101] op_sel_hi:[1,0]
	v_pk_add_f32 v[214:215], v[214:215], s[100:101] op_sel_hi:[1,0]
	v_pk_add_f32 v[216:217], v[216:217], s[100:101] op_sel_hi:[1,0]
	v_pk_add_f32 v[218:219], v[218:219], s[100:101] op_sel_hi:[1,0]
	v_rcp_f32_e32 v212, v212
	v_rcp_f32_e32 v213, v213
	v_rcp_f32_e32 v214, v214
	v_rcp_f32_e32 v215, v215
	v_rcp_f32_e32 v216, v216
	v_rcp_f32_e32 v217, v217
	v_rcp_f32_e32 v218, v218
	v_rcp_f32_e32 v219, v219
	v_pk_mul_f32 v[90:91], v[84:85], v[212:213]
	v_pk_mul_f32 v[88:89], v[86:87], v[214:215]
	v_pk_mul_f32 v[92:93], v[82:83], v[216:217]
	v_pk_mul_f32 v[94:95], v[80:81], v[218:219]

; #define GAS __attribute__((address_space(1)))
; __device__ __forceinline__ float sigmoidf_(float x) { return frcp(1.f + fexp2(-x * LOG2E)); }
;     __device__ __forceinline__ void operator()(const Unit& u, int row, int col, f32x4 v0, f32x4 v1) const {
;     ...
;             if (pn >= 10) {
;                 const f32x4 b0 = *(const GAS f32x4*)(b_gate + pc - PC_GATE), b1 = *(const GAS f32x4*)(b_gate + pc - PC_GATE + 4);
; #pragma unroll
;                 for (int i = 0; i < 4; ++i) { v0[i] = sigmoidf_(v0[i] + b0[i]); v1[i] = sigmoidf_(v1[i] + b1[i]); }
.LBB0_274:
	s_andn2_b64 vcc, exec, s[74:75]
	s_cbranch_vccnz .LBB0_276
	v_pk_add_f32 v[212:213], v[80:81], v[208:209]
	v_pk_add_f32 v[214:215], v[82:83], v[210:211]
	v_pk_add_f32 v[216:217], v[84:85], v[204:205]
	v_pk_add_f32 v[218:219], v[86:87], v[206:207]
	v_pk_mul_f32 v[212:213], v[212:213], s[98:99] op_sel_hi:[1,0]
	v_pk_mul_f32 v[214:215], v[214:215], s[98:99] op_sel_hi:[1,0]
	v_pk_mul_f32 v[216:217], v[216:217], s[98:99] op_sel_hi:[1,0]
	v_pk_mul_f32 v[218:219], v[218:219], s[98:99] op_sel_hi:[1,0]
	v_exp_f32_e32 v212, v212
	v_exp_f32_e32 v213, v213
	v_exp_f32_e32 v214, v214
	v_exp_f32_e32 v215, v215
	v_exp_f32_e32 v216, v216
	v_exp_f32_e32 v217, v217
	v_exp_f32_e32 v218, v218
	v_exp_f32_e32 v219, v219
	v_pk_add_f32 v[212:213], v[212:213], s[100:101] op_sel_hi:[1,0]
	v_pk_add_f32 v[214:215], v[214:215], s[100:101] op_sel_hi:[1,0]
	v_pk_add_f32 v[216:217], v[216:217], s[100:101] op_sel_hi:[1,0]
	v_pk_add_f32 v[218:219], v[218:219], s[100:101] op_sel_hi:[1,0]
	v_rcp_f32_e32 v94, v212
	v_rcp_f32_e32 v95, v213
	v_rcp_f32_e32 v92, v214
	v_rcp_f32_e32 v93, v215
	v_rcp_f32_e32 v90, v216
	v_rcp_f32_e32 v91, v217
	v_rcp_f32_e32 v88, v218
	v_rcp_f32_e32 v89, v219

; __device__ __forceinline__ float siluf_(float x) { return x * sigmoidf_(x); }
;     __device__ __forceinline__ void operator()(const Unit& u, int row, int col, f32x4 v0, f32x4 v1) const {
;     ...
; #pragma unroll
;                 for (int i = 0; i < 4; ++i) { v0[i] = siluf_(v0[i]); v1[i] = siluf_(v1[i]); }
.LBB0_285:
	s_andn2_b64 vcc, exec, s[74:75]
	s_cbranch_vccnz .LBB0_295
	s_andn2_b64 vcc, exec, s[72:73]
	s_mov_b64 s[74:75], -1
	s_cbranch_vccnz .LBB0_292
	s_andn2_b64 vcc, exec, s[70:71]
	s_cbranch_vccnz .LBB0_289
	s_mov_b64 s[74:75], 0
	v_pk_mul_f32 v[212:213], v[76:77], s[98:99] op_sel_hi:[1,0]
	v_pk_mul_f32 v[214:215], v[78:79], s[98:99] op_sel_hi:[1,0]
	v_pk_mul_f32 v[216:217], v[74:75], s[98:99] op_sel_hi:[1,0]
	v_pk_mul_f32 v[218:219], v[72:73], s[98:99] op_sel_hi:[1,0]
	v_exp_f32_e32 v212, v212
	v_exp_f32_e32 v213, v213
	v_exp_f32_e32 v214, v214
	v_exp_f32_e32 v215, v215
	v_exp_f32_e32 v216, v216
	v_exp_f32_e32 v217, v217
	v_exp_f32_e32 v218, v218
	v_exp_f32_e32 v219, v219
	v_pk_add_f32 v[212:213], v[212:213], s[100:101] op_sel_hi:[1,0]
	v_pk_add_f32 v[214:215], v[214:215], s[100:101] op_sel_hi:[1,0]
	v_pk_add_f32 v[216:217], v[216:217], s[100:101] op_sel_hi:[1,0]
	v_pk_add_f32 v[218:219], v[218:219], s[100:101] op_sel_hi:[1,0]
	v_rcp_f32_e32 v212, v212
	v_rcp_f32_e32 v213, v213
	v_rcp_f32_e32 v214, v214
	v_rcp_f32_e32 v215, v215
	v_rcp_f32_e32 v216, v216
	v_rcp_f32_e32 v217, v217
	v_rcp_f32_e32 v218, v218
	v_rcp_f32_e32 v219, v219
	v_pk_mul_f32 v[86:87], v[76:77], v[212:213]
	v_pk_mul_f32 v[84:85], v[78:79], v[214:215]
	v_pk_mul_f32 v[88:89], v[74:75], v[216:217]
	v_pk_mul_f32 v[90:91], v[72:73], v[218:219]

; #define GAS __attribute__((address_space(1)))
; __device__ __forceinline__ float sigmoidf_(float x) { return frcp(1.f + fexp2(-x * LOG2E)); }
;     __device__ __forceinline__ void operator()(const Unit& u, int row, int col, f32x4 v0, f32x4 v1) const {
;     ...
;             if (pn >= 10) {
;                 const f32x4 b0 = *(const GAS f32x4*)(b_gate + pc - PC_GATE), b1 = *(const GAS f32x4*)(b_gate + pc - PC_GATE + 4);
; #pragma unroll
;                 for (int i = 0; i < 4; ++i) { v0[i] = sigmoidf_(v0[i] + b0[i]); v1[i] = sigmoidf_(v1[i] + b1[i]); }
.LBB0_292:
	s_andn2_b64 vcc, exec, s[74:75]
	s_cbranch_vccnz .LBB0_294
	v_pk_add_f32 v[212:213], v[72:73], v[200:201]
	v_pk_add_f32 v[214:215], v[74:75], v[202:203]
	v_pk_add_f32 v[216:217], v[76:77], v[196:197]
	v_pk_add_f32 v[218:219], v[78:79], v[198:199]
	v_pk_mul_f32 v[212:213], v[212:213], s[98:99] op_sel_hi:[1,0]
	v_pk_mul_f32 v[214:215], v[214:215], s[98:99] op_sel_hi:[1,0]
	v_pk_mul_f32 v[216:217], v[216:217], s[98:99] op_sel_hi:[1,0]
	v_pk_mul_f32 v[218:219], v[218:219], s[98:99] op_sel_hi:[1,0]
	v_exp_f32_e32 v212, v212
	v_exp_f32_e32 v213, v213
	v_exp_f32_e32 v214, v214
	v_exp_f32_e32 v215, v215
	v_exp_f32_e32 v216, v216
	v_exp_f32_e32 v217, v217
	v_exp_f32_e32 v218, v218
	v_exp_f32_e32 v219, v219
	v_pk_add_f32 v[212:213], v[212:213], s[100:101] op_sel_hi:[1,0]
	v_pk_add_f32 v[214:215], v[214:215], s[100:101] op_sel_hi:[1,0]
	v_pk_add_f32 v[216:217], v[216:217], s[100:101] op_sel_hi:[1,0]
	v_pk_add_f32 v[218:219], v[218:219], s[100:101] op_sel_hi:[1,0]
	v_rcp_f32_e32 v90, v212
	v_rcp_f32_e32 v91, v213
	v_rcp_f32_e32 v88, v214
	v_rcp_f32_e32 v89, v215
	v_rcp_f32_e32 v86, v216
	v_rcp_f32_e32 v87, v217
	v_rcp_f32_e32 v84, v218
	v_rcp_f32_e32 v85, v219

; #define GAS __attribute__((address_space(1)))
; __device__ __forceinline__ float sigmoidf_(float x) { return frcp(1.f + fexp2(-x * LOG2E)); }
; __device__ __forceinline__ float siluf_(float x) { return x * sigmoidf_(x); }
; __device__ __forceinline__ u32x4 pack8(f32x4 a, f32x4 b) { u32x4 w; w.x = pk2(a[0], a[1]); w.y = pk2(a[2], a[3]); w.z = pk2(b[0], b[1]); w.w = pk2(b[2], b[3]); return w; }
;     __device__ __forceinline__ void operator()(const Unit& u, int row, int col, f32x4 v0, f32x4 v1) const {
;     ...
;         if (pn < 2) {
;             const int c = pn * 256 + col, g = c >> 4, p = c & 15;
;             *(GAS u32x4*)(Ap + ((size_t)(g * 2048 + (row >> 4)) * 512 + (row & 15) * 16 + p)) = pack8(v0, v1);
;         } else if (pn < 22) {
;             const int pc = pn * 256 - 512 + col;
;             if (pn >= 10) {
;                 const f32x4 b0 = *(const GAS f32x4*)(b_gate + pc - PC_GATE), b1 = *(const GAS f32x4*)(b_gate + pc - PC_GATE + 4);
; #pragma unroll
;                 for (int i = 0; i < 4; ++i) { v0[i] = sigmoidf_(v0[i] + b0[i]); v1[i] = sigmoidf_(v1[i] + b1[i]); }
;             } else if (pn == 8 || pn == 9) {
;                 const float sc = 0.08838834764831845f * LOG2E;
;                 v0 = v0 * sc; v1 = v1 * sc;
;             } else {
; #pragma unroll
;                 for (int i = 0; i < 4; ++i) { v0[i] = siluf_(v0[i]); v1[i] = siluf_(v1[i]); }
;             }
;             __builtin_nontemporal_store(pack8(v0, v1), (GAS u32x4*)(P + (size_t)row * PW + pc));
.LBB0_299:
	s_andn2_b64 vcc, exec, s[74:75]
	s_cbranch_vccnz .LBB0_309
	s_andn2_b64 vcc, exec, s[72:73]
	s_mov_b64 s[74:75], -1
	s_cbranch_vccnz .LBB0_306
	s_andn2_b64 vcc, exec, s[70:71]
	s_cbranch_vccnz .LBB0_303
	s_mov_b64 s[74:75], 0
	v_pk_mul_f32 v[212:213], v[68:69], s[98:99] op_sel_hi:[1,0]
	v_pk_mul_f32 v[214:215], v[70:71], s[98:99] op_sel_hi:[1,0]
	v_pk_mul_f32 v[216:217], v[66:67], s[98:99] op_sel_hi:[1,0]
	v_pk_mul_f32 v[218:219], v[64:65], s[98:99] op_sel_hi:[1,0]
	v_exp_f32_e32 v212, v212
	v_exp_f32_e32 v213, v213
	v_exp_f32_e32 v214, v214
	v_exp_f32_e32 v215, v215
	v_exp_f32_e32 v216, v216
	v_exp_f32_e32 v217, v217
	v_exp_f32_e32 v218, v218
	v_exp_f32_e32 v219, v219
	v_pk_add_f32 v[212:213], v[212:213], s[100:101] op_sel_hi:[1,0]
	v_pk_add_f32 v[214:215], v[214:215], s[100:101] op_sel_hi:[1,0]
	v_pk_add_f32 v[216:217], v[216:217], s[100:101] op_sel_hi:[1,0]
	v_pk_add_f32 v[218:219], v[218:219], s[100:101] op_sel_hi:[1,0]
	v_rcp_f32_e32 v212, v212
	v_rcp_f32_e32 v213, v213
	v_rcp_f32_e32 v214, v214
	v_rcp_f32_e32 v215, v215
	v_rcp_f32_e32 v216, v216
	v_rcp_f32_e32 v217, v217
	v_rcp_f32_e32 v218, v218
	v_rcp_f32_e32 v219, v219
	v_pk_mul_f32 v[74:75], v[68:69], v[212:213]
	v_pk_mul_f32 v[72:73], v[70:71], v[214:215]
	v_pk_mul_f32 v[76:77], v[66:67], v[216:217]
	v_pk_mul_f32 v[78:79], v[64:65], v[218:219]

; #define GAS __attribute__((address_space(1)))
; __device__ __forceinline__ float sigmoidf_(float x) { return frcp(1.f + fexp2(-x * LOG2E)); }
;     __device__ __forceinline__ void operator()(const Unit& u, int row, int col, f32x4 v0, f32x4 v1) const {
;     ...
;             const int pc = pn * 256 - 512 + col;
;             if (pn >= 10) {
;                 const f32x4 b0 = *(const GAS f32x4*)(b_gate + pc - PC_GATE), b1 = *(const GAS f32x4*)(b_gate + pc - PC_GATE + 4);
; #pragma unroll
;                 for (int i = 0; i < 4; ++i) { v0[i] = sigmoidf_(v0[i] + b0[i]); v1[i] = sigmoidf_(v1[i] + b1[i]); }
.LBB0_306:
	s_andn2_b64 vcc, exec, s[74:75]
	s_cbranch_vccnz .LBB0_308
	v_pk_add_f32 v[212:213], v[64:65], v[208:209]
	v_pk_add_f32 v[214:215], v[66:67], v[210:211]
	v_pk_add_f32 v[216:217], v[68:69], v[204:205]
	v_pk_add_f32 v[218:219], v[70:71], v[206:207]
	v_pk_mul_f32 v[212:213], v[212:213], s[98:99] op_sel_hi:[1,0]
	v_pk_mul_f32 v[214:215], v[214:215], s[98:99] op_sel_hi:[1,0]
	v_pk_mul_f32 v[216:217], v[216:217], s[98:99] op_sel_hi:[1,0]
	v_pk_mul_f32 v[218:219], v[218:219], s[98:99] op_sel_hi:[1,0]
	v_exp_f32_e32 v212, v212
	v_exp_f32_e32 v213, v213
	v_exp_f32_e32 v214, v214
	v_exp_f32_e32 v215, v215
	v_exp_f32_e32 v216, v216
	v_exp_f32_e32 v217, v217
	v_exp_f32_e32 v218, v218
	v_exp_f32_e32 v219, v219
	v_pk_add_f32 v[212:213], v[212:213], s[100:101] op_sel_hi:[1,0]
	v_pk_add_f32 v[214:215], v[214:215], s[100:101] op_sel_hi:[1,0]
	v_pk_add_f32 v[216:217], v[216:217], s[100:101] op_sel_hi:[1,0]
	v_pk_add_f32 v[218:219], v[218:219], s[100:101] op_sel_hi:[1,0]
	v_rcp_f32_e32 v78, v212
	v_rcp_f32_e32 v79, v213
	v_rcp_f32_e32 v76, v214
	v_rcp_f32_e32 v77, v215
	v_rcp_f32_e32 v74, v216
	v_rcp_f32_e32 v75, v217
	v_rcp_f32_e32 v72, v218
	v_rcp_f32_e32 v73, v219

; #define GAS __attribute__((address_space(1)))
; __device__ __forceinline__ float sigmoidf_(float x) { return frcp(1.f + fexp2(-x * LOG2E)); }
; __device__ __forceinline__ float siluf_(float x) { return x * sigmoidf_(x); }
; __device__ __forceinline__ u32x4 pack8(f32x4 a, f32x4 b) { u32x4 w; w.x = pk2(a[0], a[1]); w.y = pk2(a[2], a[3]); w.z = pk2(b[0], b[1]); w.w = pk2(b[2], b[3]); return w; }
;     __device__ __forceinline__ void operator()(const Unit& u, int row, int col, f32x4 v0, f32x4 v1) const {
;     ...
;         if (pn < 2) {
;             const int c = pn * 256 + col, g = c >> 4, p = c & 15;
;             *(GAS u32x4*)(Ap + ((size_t)(g * 2048 + (row >> 4)) * 512 + (row & 15) * 16 + p)) = pack8(v0, v1);
;         } else if (pn < 22) {
;             const int pc = pn * 256 - 512 + col;
;             if (pn >= 10) {
;                 const f32x4 b0 = *(const GAS f32x4*)(b_gate + pc - PC_GATE), b1 = *(const GAS f32x4*)(b_gate + pc - PC_GATE + 4);
; #pragma unroll
;                 for (int i = 0; i < 4; ++i) { v0[i] = sigmoidf_(v0[i] + b0[i]); v1[i] = sigmoidf_(v1[i] + b1[i]); }
;             } else if (pn == 8 || pn == 9) {
;                 const float sc = 0.08838834764831845f * LOG2E;
;                 v0 = v0 * sc; v1 = v1 * sc;
;             } else {
; #pragma unroll
;                 for (int i = 0; i < 4; ++i) { v0[i] = siluf_(v0[i]); v1[i] = siluf_(v1[i]); }
;             }
;             __builtin_nontemporal_store(pack8(v0, v1), (GAS u32x4*)(P + (size_t)row * PW + pc));
.LBB0_317:
	s_andn2_b64 vcc, exec, s[74:75]
	s_cbranch_vccnz .LBB0_327
	s_andn2_b64 vcc, exec, s[72:73]
	s_mov_b64 s[74:75], -1
	s_cbranch_vccnz .LBB0_324
	s_andn2_b64 vcc, exec, s[70:71]
	s_cbranch_vccnz .LBB0_321
	s_mov_b64 s[74:75], 0
	v_pk_mul_f32 v[212:213], v[60:61], s[98:99] op_sel_hi:[1,0]
	v_pk_mul_f32 v[214:215], v[62:63], s[98:99] op_sel_hi:[1,0]
	v_pk_mul_f32 v[216:217], v[58:59], s[98:99] op_sel_hi:[1,0]
	v_pk_mul_f32 v[218:219], v[56:57], s[98:99] op_sel_hi:[1,0]
	v_exp_f32_e32 v212, v212
	v_exp_f32_e32 v213, v213
	v_exp_f32_e32 v214, v214
	v_exp_f32_e32 v215, v215
	v_exp_f32_e32 v216, v216
	v_exp_f32_e32 v217, v217
	v_exp_f32_e32 v218, v218
	v_exp_f32_e32 v219, v219
	v_pk_add_f32 v[212:213], v[212:213], s[100:101] op_sel_hi:[1,0]
	v_pk_add_f32 v[214:215], v[214:215], s[100:101] op_sel_hi:[1,0]
	v_pk_add_f32 v[216:217], v[216:217], s[100:101] op_sel_hi:[1,0]
	v_pk_add_f32 v[218:219], v[218:219], s[100:101] op_sel_hi:[1,0]
	v_rcp_f32_e32 v212, v212
	v_rcp_f32_e32 v213, v213
	v_rcp_f32_e32 v214, v214
	v_rcp_f32_e32 v215, v215
	v_rcp_f32_e32 v216, v216
	v_rcp_f32_e32 v217, v217
	v_rcp_f32_e32 v218, v218
	v_rcp_f32_e32 v219, v219
	v_pk_mul_f32 v[70:71], v[60:61], v[212:213]
	v_pk_mul_f32 v[68:69], v[62:63], v[214:215]
	v_pk_mul_f32 v[72:73], v[58:59], v[216:217]
	v_pk_mul_f32 v[74:75], v[56:57], v[218:219]

; #define GAS __attribute__((address_space(1)))
; __device__ __forceinline__ float sigmoidf_(float x) { return frcp(1.f + fexp2(-x * LOG2E)); }
;     __device__ __forceinline__ void operator()(const Unit& u, int row, int col, f32x4 v0, f32x4 v1) const {
;     ...
;             const int pc = pn * 256 - 512 + col;
;             if (pn >= 10) {
;                 const f32x4 b0 = *(const GAS f32x4*)(b_gate + pc - PC_GATE), b1 = *(const GAS f32x4*)(b_gate + pc - PC_GATE + 4);
; #pragma unroll
;                 for (int i = 0; i < 4; ++i) { v0[i] = sigmoidf_(v0[i] + b0[i]); v1[i] = sigmoidf_(v1[i] + b1[i]); }
.LBB0_324:
	s_andn2_b64 vcc, exec, s[74:75]
	s_cbranch_vccnz .LBB0_326
	v_pk_add_f32 v[212:213], v[56:57], v[200:201]
	v_pk_add_f32 v[214:215], v[58:59], v[202:203]
	v_pk_add_f32 v[216:217], v[60:61], v[196:197]
	v_pk_add_f32 v[218:219], v[62:63], v[198:199]
	v_pk_mul_f32 v[212:213], v[212:213], s[98:99] op_sel_hi:[1,0]
	v_pk_mul_f32 v[214:215], v[214:215], s[98:99] op_sel_hi:[1,0]
	v_pk_mul_f32 v[216:217], v[216:217], s[98:99] op_sel_hi:[1,0]
	v_pk_mul_f32 v[218:219], v[218:219], s[98:99] op_sel_hi:[1,0]
	v_exp_f32_e32 v212, v212
	v_exp_f32_e32 v213, v213
	v_exp_f32_e32 v214, v214
	v_exp_f32_e32 v215, v215
	v_exp_f32_e32 v216, v216
	v_exp_f32_e32 v217, v217
	v_exp_f32_e32 v218, v218
	v_exp_f32_e32 v219, v219
	v_pk_add_f32 v[212:213], v[212:213], s[100:101] op_sel_hi:[1,0]
	v_pk_add_f32 v[214:215], v[214:215], s[100:101] op_sel_hi:[1,0]
	v_pk_add_f32 v[216:217], v[216:217], s[100:101] op_sel_hi:[1,0]
	v_pk_add_f32 v[218:219], v[218:219], s[100:101] op_sel_hi:[1,0]
	v_rcp_f32_e32 v74, v212
	v_rcp_f32_e32 v75, v213
	v_rcp_f32_e32 v72, v214
	v_rcp_f32_e32 v73, v215
	v_rcp_f32_e32 v70, v216
	v_rcp_f32_e32 v71, v217
	v_rcp_f32_e32 v68, v218
	v_rcp_f32_e32 v69, v219

; #define GAS __attribute__((address_space(1)))
; __device__ __forceinline__ float sigmoidf_(float x) { return frcp(1.f + fexp2(-x * LOG2E)); }
; __device__ __forceinline__ float siluf_(float x) { return x * sigmoidf_(x); }
; __device__ __forceinline__ u32x4 pack8(f32x4 a, f32x4 b) { u32x4 w; w.x = pk2(a[0], a[1]); w.y = pk2(a[2], a[3]); w.z = pk2(b[0], b[1]); w.w = pk2(b[2], b[3]); return w; }
;     __device__ __forceinline__ void operator()(const Unit& u, int row, int col, f32x4 v0, f32x4 v1) const {
;     ...
;         if (pn < 2) {
;             const int c = pn * 256 + col, g = c >> 4, p = c & 15;
;             *(GAS u32x4*)(Ap + ((size_t)(g * 2048 + (row >> 4)) * 512 + (row & 15) * 16 + p)) = pack8(v0, v1);
;         } else if (pn < 22) {
;             const int pc = pn * 256 - 512 + col;
;             if (pn >= 10) {
;                 const f32x4 b0 = *(const GAS f32x4*)(b_gate + pc - PC_GATE), b1 = *(const GAS f32x4*)(b_gate + pc - PC_GATE + 4);
; #pragma unroll
;                 for (int i = 0; i < 4; ++i) { v0[i] = sigmoidf_(v0[i] + b0[i]); v1[i] = sigmoidf_(v1[i] + b1[i]); }
;             } else if (pn == 8 || pn == 9) {
;                 const float sc = 0.08838834764831845f * LOG2E;
;                 v0 = v0 * sc; v1 = v1 * sc;
;             } else {
; #pragma unroll
;                 for (int i = 0; i < 4; ++i) { v0[i] = siluf_(v0[i]); v1[i] = siluf_(v1[i]); }
;             }
;             __builtin_nontemporal_store(pack8(v0, v1), (GAS u32x4*)(P + (size_t)row * PW + pc));
.LBB0_331:
	s_andn2_b64 vcc, exec, s[74:75]
	s_cbranch_vccnz .LBB0_341
	s_andn2_b64 vcc, exec, s[72:73]
	s_mov_b64 s[74:75], -1
	s_cbranch_vccnz .LBB0_338
	s_andn2_b64 vcc, exec, s[70:71]
	s_cbranch_vccnz .LBB0_335
	s_mov_b64 s[74:75], 0
	v_pk_mul_f32 v[212:213], v[52:53], s[98:99] op_sel_hi:[1,0]
	v_pk_mul_f32 v[214:215], v[54:55], s[98:99] op_sel_hi:[1,0]
	v_pk_mul_f32 v[216:217], v[50:51], s[98:99] op_sel_hi:[1,0]
	v_pk_mul_f32 v[218:219], v[48:49], s[98:99] op_sel_hi:[1,0]
	v_exp_f32_e32 v212, v212
	v_exp_f32_e32 v213, v213
	v_exp_f32_e32 v214, v214
	v_exp_f32_e32 v215, v215
	v_exp_f32_e32 v216, v216
	v_exp_f32_e32 v217, v217
	v_exp_f32_e32 v218, v218
	v_exp_f32_e32 v219, v219
	v_pk_add_f32 v[212:213], v[212:213], s[100:101] op_sel_hi:[1,0]
	v_pk_add_f32 v[214:215], v[214:215], s[100:101] op_sel_hi:[1,0]
	v_pk_add_f32 v[216:217], v[216:217], s[100:101] op_sel_hi:[1,0]
	v_pk_add_f32 v[218:219], v[218:219], s[100:101] op_sel_hi:[1,0]
	v_rcp_f32_e32 v212, v212
	v_rcp_f32_e32 v213, v213
	v_rcp_f32_e32 v214, v214
	v_rcp_f32_e32 v215, v215
	v_rcp_f32_e32 v216, v216
	v_rcp_f32_e32 v217, v217
	v_rcp_f32_e32 v218, v218
	v_rcp_f32_e32 v219, v219
	v_pk_mul_f32 v[58:59], v[52:53], v[212:213]
	v_pk_mul_f32 v[56:57], v[54:55], v[214:215]
	v_pk_mul_f32 v[60:61], v[50:51], v[216:217]
	v_pk_mul_f32 v[62:63], v[48:49], v[218:219]

; #define GAS __attribute__((address_space(1)))
; __device__ __forceinline__ float sigmoidf_(float x) { return frcp(1.f + fexp2(-x * LOG2E)); }
;     __device__ __forceinline__ void operator()(const Unit& u, int row, int col, f32x4 v0, f32x4 v1) const {
;     ...
;             const int pc = pn * 256 - 512 + col;
;             if (pn >= 10) {
;                 const f32x4 b0 = *(const GAS f32x4*)(b_gate + pc - PC_GATE), b1 = *(const GAS f32x4*)(b_gate + pc - PC_GATE + 4);
; #pragma unroll
;                 for (int i = 0; i < 4; ++i) { v0[i] = sigmoidf_(v0[i] + b0[i]); v1[i] = sigmoidf_(v1[i] + b1[i]); }
.LBB0_338:
	s_andn2_b64 vcc, exec, s[74:75]
	s_cbranch_vccnz .LBB0_340
	v_pk_add_f32 v[212:213], v[48:49], v[208:209]
	v_pk_add_f32 v[214:215], v[50:51], v[210:211]
	v_pk_add_f32 v[216:217], v[52:53], v[204:205]
	v_pk_add_f32 v[218:219], v[54:55], v[206:207]
	v_pk_mul_f32 v[212:213], v[212:213], s[98:99] op_sel_hi:[1,0]
	v_pk_mul_f32 v[214:215], v[214:215], s[98:99] op_sel_hi:[1,0]
	v_pk_mul_f32 v[216:217], v[216:217], s[98:99] op_sel_hi:[1,0]
	v_pk_mul_f32 v[218:219], v[218:219], s[98:99] op_sel_hi:[1,0]
	v_exp_f32_e32 v212, v212
	v_exp_f32_e32 v213, v213
	v_exp_f32_e32 v214, v214
	v_exp_f32_e32 v215, v215
	v_exp_f32_e32 v216, v216
	v_exp_f32_e32 v217, v217
	v_exp_f32_e32 v218, v218
	v_exp_f32_e32 v219, v219
	v_pk_add_f32 v[212:213], v[212:213], s[100:101] op_sel_hi:[1,0]
	v_pk_add_f32 v[214:215], v[214:215], s[100:101] op_sel_hi:[1,0]
	v_pk_add_f32 v[216:217], v[216:217], s[100:101] op_sel_hi:[1,0]
	v_pk_add_f32 v[218:219], v[218:219], s[100:101] op_sel_hi:[1,0]
	v_rcp_f32_e32 v62, v212
	v_rcp_f32_e32 v63, v213
	v_rcp_f32_e32 v60, v214
	v_rcp_f32_e32 v61, v215
	v_rcp_f32_e32 v58, v216
	v_rcp_f32_e32 v59, v217
	v_rcp_f32_e32 v56, v218
	v_rcp_f32_e32 v57, v219

; #define GAS __attribute__((address_space(1)))
; __device__ __forceinline__ float sigmoidf_(float x) { return frcp(1.f + fexp2(-x * LOG2E)); }
; __device__ __forceinline__ float siluf_(float x) { return x * sigmoidf_(x); }
; __device__ __forceinline__ u32x4 pack8(f32x4 a, f32x4 b) { u32x4 w; w.x = pk2(a[0], a[1]); w.y = pk2(a[2], a[3]); w.z = pk2(b[0], b[1]); w.w = pk2(b[2], b[3]); return w; }
;     __device__ __forceinline__ void operator()(const Unit& u, int row, int col, f32x4 v0, f32x4 v1) const {
;     ...
;         if (pn < 2) {
;             const int c = pn * 256 + col, g = c >> 4, p = c & 15;
;             *(GAS u32x4*)(Ap + ((size_t)(g * 2048 + (row >> 4)) * 512 + (row & 15) * 16 + p)) = pack8(v0, v1);
;         } else if (pn < 22) {
;             const int pc = pn * 256 - 512 + col;
;             if (pn >= 10) {
;                 const f32x4 b0 = *(const GAS f32x4*)(b_gate + pc - PC_GATE), b1 = *(const GAS f32x4*)(b_gate + pc - PC_GATE + 4);
; #pragma unroll
;                 for (int i = 0; i < 4; ++i) { v0[i] = sigmoidf_(v0[i] + b0[i]); v1[i] = sigmoidf_(v1[i] + b1[i]); }
;             } else if (pn == 8 || pn == 9) {
;                 const float sc = 0.08838834764831845f * LOG2E;
;                 v0 = v0 * sc; v1 = v1 * sc;
;             } else {
; #pragma unroll
;                 for (int i = 0; i < 4; ++i) { v0[i] = siluf_(v0[i]); v1[i] = siluf_(v1[i]); }
;             }
;             __builtin_nontemporal_store(pack8(v0, v1), (GAS u32x4*)(P + (size_t)row * PW + pc));
.LBB0_349:
	s_andn2_b64 vcc, exec, s[74:75]
	s_cbranch_vccnz .LBB0_359
	s_andn2_b64 vcc, exec, s[72:73]
	s_mov_b64 s[74:75], -1
	s_cbranch_vccnz .LBB0_356
	s_andn2_b64 vcc, exec, s[70:71]
	s_cbranch_vccnz .LBB0_353
	s_mov_b64 s[74:75], 0
	v_pk_mul_f32 v[212:213], v[44:45], s[98:99] op_sel_hi:[1,0]
	v_pk_mul_f32 v[214:215], v[46:47], s[98:99] op_sel_hi:[1,0]
	v_pk_mul_f32 v[216:217], v[42:43], s[98:99] op_sel_hi:[1,0]
	v_pk_mul_f32 v[218:219], v[40:41], s[98:99] op_sel_hi:[1,0]
	v_exp_f32_e32 v212, v212
	v_exp_f32_e32 v213, v213
	v_exp_f32_e32 v214, v214
	v_exp_f32_e32 v215, v215
	v_exp_f32_e32 v216, v216
	v_exp_f32_e32 v217, v217
	v_exp_f32_e32 v218, v218
	v_exp_f32_e32 v219, v219
	v_pk_add_f32 v[212:213], v[212:213], s[100:101] op_sel_hi:[1,0]
	v_pk_add_f32 v[214:215], v[214:215], s[100:101] op_sel_hi:[1,0]
	v_pk_add_f32 v[216:217], v[216:217], s[100:101] op_sel_hi:[1,0]
	v_pk_add_f32 v[218:219], v[218:219], s[100:101] op_sel_hi:[1,0]
	v_rcp_f32_e32 v212, v212
	v_rcp_f32_e32 v213, v213
	v_rcp_f32_e32 v214, v214
	v_rcp_f32_e32 v215, v215
	v_rcp_f32_e32 v216, v216
	v_rcp_f32_e32 v217, v217
	v_rcp_f32_e32 v218, v218
	v_rcp_f32_e32 v219, v219
	v_pk_mul_f32 v[54:55], v[44:45], v[212:213]
	v_pk_mul_f32 v[52:53], v[46:47], v[214:215]
	v_pk_mul_f32 v[56:57], v[42:43], v[216:217]
	v_pk_mul_f32 v[58:59], v[40:41], v[218:219]

; #define GAS __attribute__((address_space(1)))
; __device__ __forceinline__ float sigmoidf_(float x) { return frcp(1.f + fexp2(-x * LOG2E)); }
;     __device__ __forceinline__ void operator()(const Unit& u, int row, int col, f32x4 v0, f32x4 v1) const {
;     ...
;             const int pc = pn * 256 - 512 + col;
;             if (pn >= 10) {
;                 const f32x4 b0 = *(const GAS f32x4*)(b_gate + pc - PC_GATE), b1 = *(const GAS f32x4*)(b_gate + pc - PC_GATE + 4);
; #pragma unroll
;                 for (int i = 0; i < 4; ++i) { v0[i] = sigmoidf_(v0[i] + b0[i]); v1[i] = sigmoidf_(v1[i] + b1[i]); }
.LBB0_356:
	s_andn2_b64 vcc, exec, s[74:75]
	s_cbranch_vccnz .LBB0_358
	v_pk_add_f32 v[212:213], v[40:41], v[200:201]
	v_pk_add_f32 v[214:215], v[42:43], v[202:203]
	v_pk_add_f32 v[216:217], v[44:45], v[196:197]
	v_pk_add_f32 v[218:219], v[46:47], v[198:199]
	v_pk_mul_f32 v[212:213], v[212:213], s[98:99] op_sel_hi:[1,0]
	v_pk_mul_f32 v[214:215], v[214:215], s[98:99] op_sel_hi:[1,0]
	v_pk_mul_f32 v[216:217], v[216:217], s[98:99] op_sel_hi:[1,0]
	v_pk_mul_f32 v[218:219], v[218:219], s[98:99] op_sel_hi:[1,0]
	v_exp_f32_e32 v212, v212
	v_exp_f32_e32 v213, v213
	v_exp_f32_e32 v214, v214
	v_exp_f32_e32 v215, v215
	v_exp_f32_e32 v216, v216
	v_exp_f32_e32 v217, v217
	v_exp_f32_e32 v218, v218
	v_exp_f32_e32 v219, v219
	v_pk_add_f32 v[212:213], v[212:213], s[100:101] op_sel_hi:[1,0]
	v_pk_add_f32 v[214:215], v[214:215], s[100:101] op_sel_hi:[1,0]
	v_pk_add_f32 v[216:217], v[216:217], s[100:101] op_sel_hi:[1,0]
	v_pk_add_f32 v[218:219], v[218:219], s[100:101] op_sel_hi:[1,0]
	v_rcp_f32_e32 v58, v212
	v_rcp_f32_e32 v59, v213
	v_rcp_f32_e32 v56, v214
	v_rcp_f32_e32 v57, v215
	v_rcp_f32_e32 v54, v216
	v_rcp_f32_e32 v55, v217
	v_rcp_f32_e32 v52, v218
	v_rcp_f32_e32 v53, v219

; #define GAS __attribute__((address_space(1)))
; __device__ __forceinline__ float sigmoidf_(float x) { return frcp(1.f + fexp2(-x * LOG2E)); }
; __device__ __forceinline__ float siluf_(float x) { return x * sigmoidf_(x); }
; __device__ __forceinline__ u32x4 pack8(f32x4 a, f32x4 b) { u32x4 w; w.x = pk2(a[0], a[1]); w.y = pk2(a[2], a[3]); w.z = pk2(b[0], b[1]); w.w = pk2(b[2], b[3]); return w; }
;     __device__ __forceinline__ void operator()(const Unit& u, int row, int col, f32x4 v0, f32x4 v1) const {
;     ...
;         if (pn < 2) {
;             const int c = pn * 256 + col, g = c >> 4, p = c & 15;
;             *(GAS u32x4*)(Ap + ((size_t)(g * 2048 + (row >> 4)) * 512 + (row & 15) * 16 + p)) = pack8(v0, v1);
;         } else if (pn < 22) {
;             const int pc = pn * 256 - 512 + col;
;             if (pn >= 10) {
;                 const f32x4 b0 = *(const GAS f32x4*)(b_gate + pc - PC_GATE), b1 = *(const GAS f32x4*)(b_gate + pc - PC_GATE + 4);
; #pragma unroll
;                 for (int i = 0; i < 4; ++i) { v0[i] = sigmoidf_(v0[i] + b0[i]); v1[i] = sigmoidf_(v1[i] + b1[i]); }
;             } else if (pn == 8 || pn == 9) {
;                 const float sc = 0.08838834764831845f * LOG2E;
;                 v0 = v0 * sc; v1 = v1 * sc;
;             } else {
; #pragma unroll
;                 for (int i = 0; i < 4; ++i) { v0[i] = siluf_(v0[i]); v1[i] = siluf_(v1[i]); }
;             }
;             __builtin_nontemporal_store(pack8(v0, v1), (GAS u32x4*)(P + (size_t)row * PW + pc));
.LBB0_363:
	s_andn2_b64 vcc, exec, s[74:75]
	s_cbranch_vccnz .LBB0_373
	s_andn2_b64 vcc, exec, s[72:73]
	s_mov_b64 s[74:75], -1
	s_cbranch_vccnz .LBB0_370
	s_andn2_b64 vcc, exec, s[70:71]
	s_cbranch_vccnz .LBB0_367
	s_mov_b64 s[74:75], 0
	v_pk_mul_f32 v[212:213], v[36:37], s[98:99] op_sel_hi:[1,0]
	v_pk_mul_f32 v[214:215], v[38:39], s[98:99] op_sel_hi:[1,0]
	v_pk_mul_f32 v[216:217], v[34:35], s[98:99] op_sel_hi:[1,0]
	v_pk_mul_f32 v[218:219], v[32:33], s[98:99] op_sel_hi:[1,0]
	v_exp_f32_e32 v212, v212
	v_exp_f32_e32 v213, v213
	v_exp_f32_e32 v214, v214
	v_exp_f32_e32 v215, v215
	v_exp_f32_e32 v216, v216
	v_exp_f32_e32 v217, v217
	v_exp_f32_e32 v218, v218
	v_exp_f32_e32 v219, v219
	v_pk_add_f32 v[212:213], v[212:213], s[100:101] op_sel_hi:[1,0]
	v_pk_add_f32 v[214:215], v[214:215], s[100:101] op_sel_hi:[1,0]
	v_pk_add_f32 v[216:217], v[216:217], s[100:101] op_sel_hi:[1,0]
	v_pk_add_f32 v[218:219], v[218:219], s[100:101] op_sel_hi:[1,0]
	v_rcp_f32_e32 v212, v212
	v_rcp_f32_e32 v213, v213
	v_rcp_f32_e32 v214, v214
	v_rcp_f32_e32 v215, v215
	v_rcp_f32_e32 v216, v216
	v_rcp_f32_e32 v217, v217
	v_rcp_f32_e32 v218, v218
	v_rcp_f32_e32 v219, v219
	v_pk_mul_f32 v[42:43], v[36:37], v[212:213]
	v_pk_mul_f32 v[40:41], v[38:39], v[214:215]
	v_pk_mul_f32 v[44:45], v[34:35], v[216:217]
	v_pk_mul_f32 v[46:47], v[32:33], v[218:219]

; #define GAS __attribute__((address_space(1)))
; __device__ __forceinline__ float sigmoidf_(float x) { return frcp(1.f + fexp2(-x * LOG2E)); }
;     __device__ __forceinline__ void operator()(const Unit& u, int row, int col, f32x4 v0, f32x4 v1) const {
;     ...
;             const int pc = pn * 256 - 512 + col;
;             if (pn >= 10) {
;                 const f32x4 b0 = *(const GAS f32x4*)(b_gate + pc - PC_GATE), b1 = *(const GAS f32x4*)(b_gate + pc - PC_GATE + 4);
; #pragma unroll
;                 for (int i = 0; i < 4; ++i) { v0[i] = sigmoidf_(v0[i] + b0[i]); v1[i] = sigmoidf_(v1[i] + b1[i]); }
.LBB0_370:
	s_andn2_b64 vcc, exec, s[74:75]
	s_cbranch_vccnz .LBB0_372
	v_pk_add_f32 v[212:213], v[32:33], v[208:209]
	v_pk_add_f32 v[214:215], v[34:35], v[210:211]
	v_pk_add_f32 v[216:217], v[36:37], v[204:205]
	v_pk_add_f32 v[218:219], v[38:39], v[206:207]
	v_pk_mul_f32 v[212:213], v[212:213], s[98:99] op_sel_hi:[1,0]
	v_pk_mul_f32 v[214:215], v[214:215], s[98:99] op_sel_hi:[1,0]
	v_pk_mul_f32 v[216:217], v[216:217], s[98:99] op_sel_hi:[1,0]
	v_pk_mul_f32 v[218:219], v[218:219], s[98:99] op_sel_hi:[1,0]
	v_exp_f32_e32 v212, v212
	v_exp_f32_e32 v213, v213
	v_exp_f32_e32 v214, v214
	v_exp_f32_e32 v215, v215
	v_exp_f32_e32 v216, v216
	v_exp_f32_e32 v217, v217
	v_exp_f32_e32 v218, v218
	v_exp_f32_e32 v219, v219
	v_pk_add_f32 v[212:213], v[212:213], s[100:101] op_sel_hi:[1,0]
	v_pk_add_f32 v[214:215], v[214:215], s[100:101] op_sel_hi:[1,0]
	v_pk_add_f32 v[216:217], v[216:217], s[100:101] op_sel_hi:[1,0]
	v_pk_add_f32 v[218:219], v[218:219], s[100:101] op_sel_hi:[1,0]
	v_rcp_f32_e32 v46, v212
	v_rcp_f32_e32 v47, v213
	v_rcp_f32_e32 v44, v214
	v_rcp_f32_e32 v45, v215
	v_rcp_f32_e32 v42, v216
	v_rcp_f32_e32 v43, v217
	v_rcp_f32_e32 v40, v218
	v_rcp_f32_e32 v41, v219

; #define GAS __attribute__((address_space(1)))
; __device__ __forceinline__ float sigmoidf_(float x) { return frcp(1.f + fexp2(-x * LOG2E)); }
; __device__ __forceinline__ float siluf_(float x) { return x * sigmoidf_(x); }
; __device__ __forceinline__ u32x4 pack8(f32x4 a, f32x4 b) { u32x4 w; w.x = pk2(a[0], a[1]); w.y = pk2(a[2], a[3]); w.z = pk2(b[0], b[1]); w.w = pk2(b[2], b[3]); return w; }
;     __device__ __forceinline__ void operator()(const Unit& u, int row, int col, f32x4 v0, f32x4 v1) const {
;     ...
;         if (pn < 2) {
;             const int c = pn * 256 + col, g = c >> 4, p = c & 15;
;             *(GAS u32x4*)(Ap + ((size_t)(g * 2048 + (row >> 4)) * 512 + (row & 15) * 16 + p)) = pack8(v0, v1);
;         } else if (pn < 22) {
;             const int pc = pn * 256 - 512 + col;
;             if (pn >= 10) {
;                 const f32x4 b0 = *(const GAS f32x4*)(b_gate + pc - PC_GATE), b1 = *(const GAS f32x4*)(b_gate + pc - PC_GATE + 4);
; #pragma unroll
;                 for (int i = 0; i < 4; ++i) { v0[i] = sigmoidf_(v0[i] + b0[i]); v1[i] = sigmoidf_(v1[i] + b1[i]); }
;             } else if (pn == 8 || pn == 9) {
;                 const float sc = 0.08838834764831845f * LOG2E;
;                 v0 = v0 * sc; v1 = v1 * sc;
;             } else {
; #pragma unroll
;                 for (int i = 0; i < 4; ++i) { v0[i] = siluf_(v0[i]); v1[i] = siluf_(v1[i]); }
;             }
;             __builtin_nontemporal_store(pack8(v0, v1), (GAS u32x4*)(P + (size_t)row * PW + pc));
.LBB0_381:
	s_andn2_b64 vcc, exec, s[74:75]
	s_cbranch_vccnz .LBB0_391
	s_andn2_b64 vcc, exec, s[72:73]
	s_mov_b64 s[74:75], -1
	s_cbranch_vccnz .LBB0_388
	s_andn2_b64 vcc, exec, s[70:71]
	s_cbranch_vccnz .LBB0_385
	s_mov_b64 s[74:75], 0
	v_pk_mul_f32 v[212:213], v[28:29], s[98:99] op_sel_hi:[1,0]
	v_pk_mul_f32 v[214:215], v[30:31], s[98:99] op_sel_hi:[1,0]
	v_pk_mul_f32 v[216:217], v[26:27], s[98:99] op_sel_hi:[1,0]
	v_pk_mul_f32 v[218:219], v[24:25], s[98:99] op_sel_hi:[1,0]
	v_exp_f32_e32 v212, v212
	v_exp_f32_e32 v213, v213
	v_exp_f32_e32 v214, v214
	v_exp_f32_e32 v215, v215
	v_exp_f32_e32 v216, v216
	v_exp_f32_e32 v217, v217
	v_exp_f32_e32 v218, v218
	v_exp_f32_e32 v219, v219
	v_pk_add_f32 v[212:213], v[212:213], s[100:101] op_sel_hi:[1,0]
	v_pk_add_f32 v[214:215], v[214:215], s[100:101] op_sel_hi:[1,0]
	v_pk_add_f32 v[216:217], v[216:217], s[100:101] op_sel_hi:[1,0]
	v_pk_add_f32 v[218:219], v[218:219], s[100:101] op_sel_hi:[1,0]
	v_rcp_f32_e32 v212, v212
	v_rcp_f32_e32 v213, v213
	v_rcp_f32_e32 v214, v214
	v_rcp_f32_e32 v215, v215
	v_rcp_f32_e32 v216, v216
	v_rcp_f32_e32 v217, v217
	v_rcp_f32_e32 v218, v218
	v_rcp_f32_e32 v219, v219
	v_pk_mul_f32 v[38:39], v[28:29], v[212:213]
	v_pk_mul_f32 v[36:37], v[30:31], v[214:215]
	v_pk_mul_f32 v[40:41], v[26:27], v[216:217]
	v_pk_mul_f32 v[42:43], v[24:25], v[218:219]

; #define GAS __attribute__((address_space(1)))
; __device__ __forceinline__ float sigmoidf_(float x) { return frcp(1.f + fexp2(-x * LOG2E)); }
;     __device__ __forceinline__ void operator()(const Unit& u, int row, int col, f32x4 v0, f32x4 v1) const {
;     ...
;             const int pc = pn * 256 - 512 + col;
;             if (pn >= 10) {
;                 const f32x4 b0 = *(const GAS f32x4*)(b_gate + pc - PC_GATE), b1 = *(const GAS f32x4*)(b_gate + pc - PC_GATE + 4);
; #pragma unroll
;                 for (int i = 0; i < 4; ++i) { v0[i] = sigmoidf_(v0[i] + b0[i]); v1[i] = sigmoidf_(v1[i] + b1[i]); }
.LBB0_388:
	s_andn2_b64 vcc, exec, s[74:75]
	s_cbranch_vccnz .LBB0_390
	v_pk_add_f32 v[212:213], v[24:25], v[200:201]
	v_pk_add_f32 v[214:215], v[26:27], v[202:203]
	v_pk_add_f32 v[216:217], v[28:29], v[196:197]
	v_pk_add_f32 v[218:219], v[30:31], v[198:199]
	v_pk_mul_f32 v[212:213], v[212:213], s[98:99] op_sel_hi:[1,0]
	v_pk_mul_f32 v[214:215], v[214:215], s[98:99] op_sel_hi:[1,0]
	v_pk_mul_f32 v[216:217], v[216:217], s[98:99] op_sel_hi:[1,0]
	v_pk_mul_f32 v[218:219], v[218:219], s[98:99] op_sel_hi:[1,0]
	v_exp_f32_e32 v212, v212
	v_exp_f32_e32 v213, v213
	v_exp_f32_e32 v214, v214
	v_exp_f32_e32 v215, v215
	v_exp_f32_e32 v216, v216
	v_exp_f32_e32 v217, v217
	v_exp_f32_e32 v218, v218
	v_exp_f32_e32 v219, v219
	v_pk_add_f32 v[212:213], v[212:213], s[100:101] op_sel_hi:[1,0]
	v_pk_add_f32 v[214:215], v[214:215], s[100:101] op_sel_hi:[1,0]
	v_pk_add_f32 v[216:217], v[216:217], s[100:101] op_sel_hi:[1,0]
	v_pk_add_f32 v[218:219], v[218:219], s[100:101] op_sel_hi:[1,0]
	v_rcp_f32_e32 v42, v212
	v_rcp_f32_e32 v43, v213
	v_rcp_f32_e32 v40, v214
	v_rcp_f32_e32 v41, v215
	v_rcp_f32_e32 v38, v216
	v_rcp_f32_e32 v39, v217
	v_rcp_f32_e32 v36, v218
	v_rcp_f32_e32 v37, v219

; #define GAS __attribute__((address_space(1)))
; __device__ __forceinline__ float sigmoidf_(float x) { return frcp(1.f + fexp2(-x * LOG2E)); }
; __device__ __forceinline__ float siluf_(float x) { return x * sigmoidf_(x); }
; __device__ __forceinline__ u32x4 pack8(f32x4 a, f32x4 b) { u32x4 w; w.x = pk2(a[0], a[1]); w.y = pk2(a[2], a[3]); w.z = pk2(b[0], b[1]); w.w = pk2(b[2], b[3]); return w; }
;     __device__ __forceinline__ void operator()(const Unit& u, int row, int col, f32x4 v0, f32x4 v1) const {
;     ...
;         if (pn < 2) {
;             const int c = pn * 256 + col, g = c >> 4, p = c & 15;
;             *(GAS u32x4*)(Ap + ((size_t)(g * 2048 + (row >> 4)) * 512 + (row & 15) * 16 + p)) = pack8(v0, v1);
;         } else if (pn < 22) {
;             const int pc = pn * 256 - 512 + col;
;             if (pn >= 10) {
;                 const f32x4 b0 = *(const GAS f32x4*)(b_gate + pc - PC_GATE), b1 = *(const GAS f32x4*)(b_gate + pc - PC_GATE + 4);
; #pragma unroll
;                 for (int i = 0; i < 4; ++i) { v0[i] = sigmoidf_(v0[i] + b0[i]); v1[i] = sigmoidf_(v1[i] + b1[i]); }
;             } else if (pn == 8 || pn == 9) {
;                 const float sc = 0.08838834764831845f * LOG2E;
;                 v0 = v0 * sc; v1 = v1 * sc;
;             } else {
; #pragma unroll
;                 for (int i = 0; i < 4; ++i) { v0[i] = siluf_(v0[i]); v1[i] = siluf_(v1[i]); }
;             }
;             __builtin_nontemporal_store(pack8(v0, v1), (GAS u32x4*)(P + (size_t)row * PW + pc));
.LBB0_395:
	s_andn2_b64 vcc, exec, s[74:75]
	s_cbranch_vccnz .LBB0_405
	s_andn2_b64 vcc, exec, s[72:73]
	s_mov_b64 s[74:75], -1
	s_cbranch_vccnz .LBB0_402
	s_andn2_b64 vcc, exec, s[70:71]
	s_cbranch_vccnz .LBB0_399
	s_mov_b64 s[74:75], 0
	v_pk_mul_f32 v[212:213], v[20:21], s[98:99] op_sel_hi:[1,0]
	v_pk_mul_f32 v[214:215], v[22:23], s[98:99] op_sel_hi:[1,0]
	v_pk_mul_f32 v[216:217], v[18:19], s[98:99] op_sel_hi:[1,0]
	v_pk_mul_f32 v[218:219], v[16:17], s[98:99] op_sel_hi:[1,0]
	v_exp_f32_e32 v212, v212
	v_exp_f32_e32 v213, v213
	v_exp_f32_e32 v214, v214
	v_exp_f32_e32 v215, v215
	v_exp_f32_e32 v216, v216
	v_exp_f32_e32 v217, v217
	v_exp_f32_e32 v218, v218
	v_exp_f32_e32 v219, v219
	v_pk_add_f32 v[212:213], v[212:213], s[100:101] op_sel_hi:[1,0]
	v_pk_add_f32 v[214:215], v[214:215], s[100:101] op_sel_hi:[1,0]
	v_pk_add_f32 v[216:217], v[216:217], s[100:101] op_sel_hi:[1,0]
	v_pk_add_f32 v[218:219], v[218:219], s[100:101] op_sel_hi:[1,0]
	v_rcp_f32_e32 v212, v212
	v_rcp_f32_e32 v213, v213
	v_rcp_f32_e32 v214, v214
	v_rcp_f32_e32 v215, v215
	v_rcp_f32_e32 v216, v216
	v_rcp_f32_e32 v217, v217
	v_rcp_f32_e32 v218, v218
	v_rcp_f32_e32 v219, v219
	v_pk_mul_f32 v[26:27], v[20:21], v[212:213]
	v_pk_mul_f32 v[24:25], v[22:23], v[214:215]
	v_pk_mul_f32 v[28:29], v[18:19], v[216:217]
	v_pk_mul_f32 v[30:31], v[16:17], v[218:219]

; #define GAS __attribute__((address_space(1)))
; __device__ __forceinline__ float sigmoidf_(float x) { return frcp(1.f + fexp2(-x * LOG2E)); }
;     __device__ __forceinline__ void operator()(const Unit& u, int row, int col, f32x4 v0, f32x4 v1) const {
;     ...
;             const int pc = pn * 256 - 512 + col;
;             if (pn >= 10) {
;                 const f32x4 b0 = *(const GAS f32x4*)(b_gate + pc - PC_GATE), b1 = *(const GAS f32x4*)(b_gate + pc - PC_GATE + 4);
; #pragma unroll
;                 for (int i = 0; i < 4; ++i) { v0[i] = sigmoidf_(v0[i] + b0[i]); v1[i] = sigmoidf_(v1[i] + b1[i]); }
.LBB0_402:
	s_andn2_b64 vcc, exec, s[74:75]
	s_cbranch_vccnz .LBB0_404
	v_pk_add_f32 v[212:213], v[16:17], v[208:209]
	v_pk_add_f32 v[214:215], v[18:19], v[210:211]
	v_pk_add_f32 v[216:217], v[20:21], v[204:205]
	v_pk_add_f32 v[218:219], v[22:23], v[206:207]
	v_pk_mul_f32 v[212:213], v[212:213], s[98:99] op_sel_hi:[1,0]
	v_pk_mul_f32 v[214:215], v[214:215], s[98:99] op_sel_hi:[1,0]
	v_pk_mul_f32 v[216:217], v[216:217], s[98:99] op_sel_hi:[1,0]
	v_pk_mul_f32 v[218:219], v[218:219], s[98:99] op_sel_hi:[1,0]
	v_exp_f32_e32 v212, v212
	v_exp_f32_e32 v213, v213
	v_exp_f32_e32 v214, v214
	v_exp_f32_e32 v215, v215
	v_exp_f32_e32 v216, v216
	v_exp_f32_e32 v217, v217
	v_exp_f32_e32 v218, v218
	v_exp_f32_e32 v219, v219
	v_pk_add_f32 v[212:213], v[212:213], s[100:101] op_sel_hi:[1,0]
	v_pk_add_f32 v[214:215], v[214:215], s[100:101] op_sel_hi:[1,0]
	v_pk_add_f32 v[216:217], v[216:217], s[100:101] op_sel_hi:[1,0]
	v_pk_add_f32 v[218:219], v[218:219], s[100:101] op_sel_hi:[1,0]
	v_rcp_f32_e32 v30, v212
	v_rcp_f32_e32 v31, v213
	v_rcp_f32_e32 v28, v214
	v_rcp_f32_e32 v29, v215
	v_rcp_f32_e32 v26, v216
	v_rcp_f32_e32 v27, v217
	v_rcp_f32_e32 v24, v218
	v_rcp_f32_e32 v25, v219

; #define GAS __attribute__((address_space(1)))
; __device__ __forceinline__ float sigmoidf_(float x) { return frcp(1.f + fexp2(-x * LOG2E)); }
; __device__ __forceinline__ float siluf_(float x) { return x * sigmoidf_(x); }
; __device__ __forceinline__ u32x4 pack8(f32x4 a, f32x4 b) { u32x4 w; w.x = pk2(a[0], a[1]); w.y = pk2(a[2], a[3]); w.z = pk2(b[0], b[1]); w.w = pk2(b[2], b[3]); return w; }
;     __device__ __forceinline__ void operator()(const Unit& u, int row, int col, f32x4 v0, f32x4 v1) const {
;     ...
;         if (pn < 2) {
;             const int c = pn * 256 + col, g = c >> 4, p = c & 15;
;             *(GAS u32x4*)(Ap + ((size_t)(g * 2048 + (row >> 4)) * 512 + (row & 15) * 16 + p)) = pack8(v0, v1);
;         } else if (pn < 22) {
;             const int pc = pn * 256 - 512 + col;
;             if (pn >= 10) {
;                 const f32x4 b0 = *(const GAS f32x4*)(b_gate + pc - PC_GATE), b1 = *(const GAS f32x4*)(b_gate + pc - PC_GATE + 4);
; #pragma unroll
;                 for (int i = 0; i < 4; ++i) { v0[i] = sigmoidf_(v0[i] + b0[i]); v1[i] = sigmoidf_(v1[i] + b1[i]); }
;             } else if (pn == 8 || pn == 9) {
;                 const float sc = 0.08838834764831845f * LOG2E;
;                 v0 = v0 * sc; v1 = v1 * sc;
;             } else {
; #pragma unroll
;                 for (int i = 0; i < 4; ++i) { v0[i] = siluf_(v0[i]); v1[i] = siluf_(v1[i]); }
;             }
;             __builtin_nontemporal_store(pack8(v0, v1), (GAS u32x4*)(P + (size_t)row * PW + pc));
.LBB0_413:
	s_andn2_b64 vcc, exec, s[74:75]
	s_cbranch_vccnz .LBB0_423
	s_andn2_b64 vcc, exec, s[72:73]
	s_mov_b64 s[74:75], -1
	s_cbranch_vccnz .LBB0_420
	s_andn2_b64 vcc, exec, s[70:71]
	s_cbranch_vccnz .LBB0_417
	s_mov_b64 s[74:75], 0
	v_pk_mul_f32 v[212:213], v[12:13], s[98:99] op_sel_hi:[1,0]
	v_pk_mul_f32 v[214:215], v[14:15], s[98:99] op_sel_hi:[1,0]
	v_pk_mul_f32 v[216:217], v[10:11], s[98:99] op_sel_hi:[1,0]
	v_pk_mul_f32 v[218:219], v[8:9], s[98:99] op_sel_hi:[1,0]
	v_exp_f32_e32 v212, v212
	v_exp_f32_e32 v213, v213
	v_exp_f32_e32 v214, v214
	v_exp_f32_e32 v215, v215
	v_exp_f32_e32 v216, v216
	v_exp_f32_e32 v217, v217
	v_exp_f32_e32 v218, v218
	v_exp_f32_e32 v219, v219
	v_pk_add_f32 v[212:213], v[212:213], s[100:101] op_sel_hi:[1,0]
	v_pk_add_f32 v[214:215], v[214:215], s[100:101] op_sel_hi:[1,0]
	v_pk_add_f32 v[216:217], v[216:217], s[100:101] op_sel_hi:[1,0]
	v_pk_add_f32 v[218:219], v[218:219], s[100:101] op_sel_hi:[1,0]
	v_rcp_f32_e32 v212, v212
	v_rcp_f32_e32 v213, v213
	v_rcp_f32_e32 v214, v214
	v_rcp_f32_e32 v215, v215
	v_rcp_f32_e32 v216, v216
	v_rcp_f32_e32 v217, v217
	v_rcp_f32_e32 v218, v218
	v_rcp_f32_e32 v219, v219
	v_pk_mul_f32 v[22:23], v[12:13], v[212:213]
	v_pk_mul_f32 v[20:21], v[14:15], v[214:215]
	v_pk_mul_f32 v[24:25], v[10:11], v[216:217]
	v_pk_mul_f32 v[26:27], v[8:9], v[218:219]

; #define GAS __attribute__((address_space(1)))
; __device__ __forceinline__ float sigmoidf_(float x) { return frcp(1.f + fexp2(-x * LOG2E)); }
;     __device__ __forceinline__ void operator()(const Unit& u, int row, int col, f32x4 v0, f32x4 v1) const {
;     ...
;             const int pc = pn * 256 - 512 + col;
;             if (pn >= 10) {
;                 const f32x4 b0 = *(const GAS f32x4*)(b_gate + pc - PC_GATE), b1 = *(const GAS f32x4*)(b_gate + pc - PC_GATE + 4);
; #pragma unroll
;                 for (int i = 0; i < 4; ++i) { v0[i] = sigmoidf_(v0[i] + b0[i]); v1[i] = sigmoidf_(v1[i] + b1[i]); }
.LBB0_420:
	s_andn2_b64 vcc, exec, s[74:75]
	s_cbranch_vccnz .LBB0_422
	v_pk_add_f32 v[212:213], v[8:9], v[200:201]
	v_pk_add_f32 v[214:215], v[10:11], v[202:203]
	v_pk_add_f32 v[216:217], v[12:13], v[196:197]
	v_pk_add_f32 v[218:219], v[14:15], v[198:199]
	v_pk_mul_f32 v[212:213], v[212:213], s[98:99] op_sel_hi:[1,0]
	v_pk_mul_f32 v[214:215], v[214:215], s[98:99] op_sel_hi:[1,0]
	v_pk_mul_f32 v[216:217], v[216:217], s[98:99] op_sel_hi:[1,0]
	v_pk_mul_f32 v[218:219], v[218:219], s[98:99] op_sel_hi:[1,0]
	v_exp_f32_e32 v212, v212
	v_exp_f32_e32 v213, v213
	v_exp_f32_e32 v214, v214
	v_exp_f32_e32 v215, v215
	v_exp_f32_e32 v216, v216
	v_exp_f32_e32 v217, v217
	v_exp_f32_e32 v218, v218
	v_exp_f32_e32 v219, v219
	v_pk_add_f32 v[212:213], v[212:213], s[100:101] op_sel_hi:[1,0]
	v_pk_add_f32 v[214:215], v[214:215], s[100:101] op_sel_hi:[1,0]
	v_pk_add_f32 v[216:217], v[216:217], s[100:101] op_sel_hi:[1,0]
	v_pk_add_f32 v[218:219], v[218:219], s[100:101] op_sel_hi:[1,0]
	v_rcp_f32_e32 v26, v212
	v_rcp_f32_e32 v27, v213
	v_rcp_f32_e32 v24, v214
	v_rcp_f32_e32 v25, v215
	v_rcp_f32_e32 v22, v216
	v_rcp_f32_e32 v23, v217
	v_rcp_f32_e32 v20, v218
	v_rcp_f32_e32 v21, v219

; #define GAS __attribute__((address_space(1)))
; __device__ __forceinline__ float sigmoidf_(float x) { return frcp(1.f + fexp2(-x * LOG2E)); }
; __device__ __forceinline__ float siluf_(float x) { return x * sigmoidf_(x); }
; __device__ __forceinline__ u32x4 pack8(f32x4 a, f32x4 b) { u32x4 w; w.x = pk2(a[0], a[1]); w.y = pk2(a[2], a[3]); w.z = pk2(b[0], b[1]); w.w = pk2(b[2], b[3]); return w; }
;     __device__ __forceinline__ void operator()(const Unit& u, int row, int col, f32x4 v0, f32x4 v1) const {
;     ...
;         if (pn < 2) {
;             const int c = pn * 256 + col, g = c >> 4, p = c & 15;
;             *(GAS u32x4*)(Ap + ((size_t)(g * 2048 + (row >> 4)) * 512 + (row & 15) * 16 + p)) = pack8(v0, v1);
;         } else if (pn < 22) {
;             const int pc = pn * 256 - 512 + col;
;             if (pn >= 10) {
;                 const f32x4 b0 = *(const GAS f32x4*)(b_gate + pc - PC_GATE), b1 = *(const GAS f32x4*)(b_gate + pc - PC_GATE + 4);
; #pragma unroll
;                 for (int i = 0; i < 4; ++i) { v0[i] = sigmoidf_(v0[i] + b0[i]); v1[i] = sigmoidf_(v1[i] + b1[i]); }
;             } else if (pn == 8 || pn == 9) {
;                 const float sc = 0.08838834764831845f * LOG2E;
;                 v0 = v0 * sc; v1 = v1 * sc;
;             } else {
; #pragma unroll
;                 for (int i = 0; i < 4; ++i) { v0[i] = siluf_(v0[i]); v1[i] = siluf_(v1[i]); }
;             }
;             __builtin_nontemporal_store(pack8(v0, v1), (GAS u32x4*)(P + (size_t)row * PW + pc));
.LBB0_427:
	s_andn2_b64 vcc, exec, s[6:7]
	s_cbranch_vccnz .LBB0_437
	s_andn2_b64 vcc, exec, s[72:73]
	s_mov_b64 s[6:7], -1
	s_cbranch_vccnz .LBB0_434
	s_andn2_b64 vcc, exec, s[70:71]
	s_cbranch_vccnz .LBB0_431
	s_mov_b64 s[6:7], 0
	v_pk_mul_f32 v[212:213], v[4:5], s[98:99] op_sel_hi:[1,0]
	v_pk_mul_f32 v[214:215], v[6:7], s[98:99] op_sel_hi:[1,0]
	v_pk_mul_f32 v[216:217], v[2:3], s[98:99] op_sel_hi:[1,0]
	v_pk_mul_f32 v[218:219], v[0:1], s[98:99] op_sel_hi:[1,0]
	v_exp_f32_e32 v212, v212
	v_exp_f32_e32 v213, v213
	v_exp_f32_e32 v214, v214
	v_exp_f32_e32 v215, v215
	v_exp_f32_e32 v216, v216
	v_exp_f32_e32 v217, v217
	v_exp_f32_e32 v218, v218
	v_exp_f32_e32 v219, v219
	v_pk_add_f32 v[212:213], v[212:213], s[100:101] op_sel_hi:[1,0]
	v_pk_add_f32 v[214:215], v[214:215], s[100:101] op_sel_hi:[1,0]
	v_pk_add_f32 v[216:217], v[216:217], s[100:101] op_sel_hi:[1,0]
	v_pk_add_f32 v[218:219], v[218:219], s[100:101] op_sel_hi:[1,0]
	v_rcp_f32_e32 v212, v212
	v_rcp_f32_e32 v213, v213
	v_rcp_f32_e32 v214, v214
	v_rcp_f32_e32 v215, v215
	v_rcp_f32_e32 v216, v216
	v_rcp_f32_e32 v217, v217
	v_rcp_f32_e32 v218, v218
	v_rcp_f32_e32 v219, v219
	v_pk_mul_f32 v[10:11], v[4:5], v[212:213]
	v_pk_mul_f32 v[8:9], v[6:7], v[214:215]
	v_pk_mul_f32 v[12:13], v[2:3], v[216:217]
	v_pk_mul_f32 v[14:15], v[0:1], v[218:219]

; #define GAS __attribute__((address_space(1)))
; __device__ __forceinline__ float sigmoidf_(float x) { return frcp(1.f + fexp2(-x * LOG2E)); }
;     __device__ __forceinline__ void operator()(const Unit& u, int row, int col, f32x4 v0, f32x4 v1) const {
;     ...
;             const int pc = pn * 256 - 512 + col;
;             if (pn >= 10) {
;                 const f32x4 b0 = *(const GAS f32x4*)(b_gate + pc - PC_GATE), b1 = *(const GAS f32x4*)(b_gate + pc - PC_GATE + 4);
; #pragma unroll
;                 for (int i = 0; i < 4; ++i) { v0[i] = sigmoidf_(v0[i] + b0[i]); v1[i] = sigmoidf_(v1[i] + b1[i]); }
.LBB0_434:
	s_andn2_b64 vcc, exec, s[6:7]
	s_cbranch_vccnz .LBB0_436
	v_pk_add_f32 v[212:213], v[0:1], v[208:209]
	v_pk_add_f32 v[214:215], v[2:3], v[210:211]
	v_pk_add_f32 v[216:217], v[4:5], v[204:205]
	v_pk_add_f32 v[218:219], v[6:7], v[206:207]
	v_pk_mul_f32 v[212:213], v[212:213], s[98:99] op_sel_hi:[1,0]
	v_pk_mul_f32 v[214:215], v[214:215], s[98:99] op_sel_hi:[1,0]
	v_pk_mul_f32 v[216:217], v[216:217], s[98:99] op_sel_hi:[1,0]
	v_pk_mul_f32 v[218:219], v[218:219], s[98:99] op_sel_hi:[1,0]
	v_exp_f32_e32 v212, v212
	v_exp_f32_e32 v213, v213
	v_exp_f32_e32 v214, v214
	v_exp_f32_e32 v215, v215
	v_exp_f32_e32 v216, v216
	v_exp_f32_e32 v217, v217
	v_exp_f32_e32 v218, v218
	v_exp_f32_e32 v219, v219
	v_pk_add_f32 v[212:213], v[212:213], s[100:101] op_sel_hi:[1,0]
	v_pk_add_f32 v[214:215], v[214:215], s[100:101] op_sel_hi:[1,0]
	v_pk_add_f32 v[216:217], v[216:217], s[100:101] op_sel_hi:[1,0]
	v_pk_add_f32 v[218:219], v[218:219], s[100:101] op_sel_hi:[1,0]
	v_rcp_f32_e32 v14, v212
	v_rcp_f32_e32 v15, v213
	v_rcp_f32_e32 v12, v214
	v_rcp_f32_e32 v13, v215
	v_rcp_f32_e32 v10, v216
	v_rcp_f32_e32 v11, v217
	v_rcp_f32_e32 v8, v218
	v_rcp_f32_e32 v9, v219
